# GQA/SWA in-proj q/k/v epilogue stores write-through (sc1) too
# baseline (speedup 1.0000x reference)
.Lq3_A:
	global_load_dwordx4 v[148:151], v133, s[24:25]
	global_load_dwordx4 v[152:155], v133, s[24:25] offset:16
	global_load_dwordx4 v[156:159], v133, s[24:25] offset:128
	global_load_dwordx4 v[160:163], v133, s[24:25] offset:144
	global_load_dwordx4 v[164:167], v131, s[8:9]
	global_load_dwordx4 v[168:171], v132, s[8:9]
	global_load_dwordx4 v[172:175], v131, s[8:9] offset:64
	global_load_dwordx4 v[176:179], v132, s[8:9] offset:64
	s_add_u32 s8, s8, 0x800
	s_addc_u32 s9, s9, 0
	global_load_dwordx4 v[202:205], v131, s[8:9]
	global_load_dwordx4 v[206:209], v132, s[8:9]
	global_load_dwordx4 v[210:213], v131, s[8:9] offset:64
	global_load_dwordx4 v[214:217], v132, s[8:9] offset:64
	v_mul_f32_e32 v134, v127, v127
	v_fmac_f32_e32 v134, v126, v126
	v_fmac_f32_e32 v134, v128, v128
	v_fmac_f32_e32 v134, v129, v129
	v_fmac_f32_e32 v134, v122, v122
	v_fmac_f32_e32 v134, v123, v123
	v_fmac_f32_e32 v134, v124, v124
	v_fmac_f32_e32 v134, v125, v125
	v_fmac_f32_e32 v134, v118, v118
	v_fmac_f32_e32 v134, v119, v119
	v_pk_mul_f32 v[136:137], v[120:121], v[120:121]
	v_pk_mul_f32 v[138:139], v[114:115], v[114:115]
	v_add_f32_e32 v134, v136, v134
	v_add_f32_e32 v134, v137, v134
	v_add_f32_e32 v134, v138, v134
	v_pk_mul_f32 v[136:137], v[116:117], v[116:117]
	v_add_f32_e32 v134, v139, v134
	v_add_f32_e32 v134, v136, v134
	v_add_f32_e32 v134, v137, v134
	ds_swizzle_b32 v135, v134 offset:swizzle(SWAP,16)
	s_waitcnt lgkmcnt(0)
	v_add_f32_e32 v134, v134, v135
	v_mov_b32_e32 v135, v134
	s_nop 1
	v_permlane32_swap_b32 v134, v135
	s_nop 1
	v_add_f32_e32 v134, v134, v135
	v_fmamk_f32 v134, v134, 0x3c800000, v242
	v_rsq_f32_e32 v134, v134
	s_waitcnt vmcnt(8)
	v_pk_mul_f32 v[136:137], v[134:135], v[148:149] op_sel_hi:[0,1]
	v_pk_mul_f32 v[126:127], v[126:127], v[136:137]
	v_pk_mul_f32 v[136:137], v[134:135], v[150:151] op_sel_hi:[0,1]
	v_pk_mul_f32 v[128:129], v[128:129], v[136:137]
	v_pk_mul_f32 v[136:137], v[134:135], v[152:153] op_sel_hi:[0,1]
	v_pk_mul_f32 v[122:123], v[122:123], v[136:137]
	v_pk_mul_f32 v[136:137], v[134:135], v[154:155] op_sel_hi:[0,1]
	v_pk_mul_f32 v[124:125], v[124:125], v[136:137]
	v_pk_mul_f32 v[136:137], v[134:135], v[156:157] op_sel_hi:[0,1]
	v_pk_mul_f32 v[118:119], v[118:119], v[136:137]
	v_pk_mul_f32 v[136:137], v[134:135], v[158:159] op_sel_hi:[0,1]
	v_pk_mul_f32 v[120:121], v[120:121], v[136:137]
	v_pk_mul_f32 v[136:137], v[134:135], v[160:161] op_sel_hi:[0,1]
	v_pk_mul_f32 v[114:115], v[114:115], v[136:137]
	v_pk_mul_f32 v[136:137], v[134:135], v[162:163] op_sel_hi:[0,1]
	v_pk_mul_f32 v[116:117], v[116:117], v[136:137]
	s_waitcnt vmcnt(4)
	v_pk_mul_f32 v[136:137], v[126:127], v[168:169] op_sel:[1,0] op_sel_hi:[0,0]
	v_pk_fma_f32 v[126:127], v[126:127], v[164:165], v[136:137] op_sel:[0,0,0] op_sel_hi:[1,0,1] neg_lo:[0,0,1]
	v_pk_mul_f32 v[136:137], v[128:129], v[168:169] op_sel:[1,1] op_sel_hi:[0,1]
	v_pk_fma_f32 v[128:129], v[128:129], v[164:165], v[136:137] op_sel:[0,1,0] op_sel_hi:[1,1,1] neg_lo:[0,0,1]
	v_pk_mul_f32 v[136:137], v[122:123], v[170:171] op_sel:[1,0] op_sel_hi:[0,0]
	v_pk_fma_f32 v[122:123], v[122:123], v[166:167], v[136:137] op_sel:[0,0,0] op_sel_hi:[1,0,1] neg_lo:[0,0,1]
	v_pk_mul_f32 v[136:137], v[124:125], v[170:171] op_sel:[1,1] op_sel_hi:[0,1]
	v_pk_fma_f32 v[124:125], v[124:125], v[166:167], v[136:137] op_sel:[0,1,0] op_sel_hi:[1,1,1] neg_lo:[0,0,1]
	v_pk_mul_f32 v[126:127], v[126:127], s[36:37] op_sel_hi:[1,0]
	v_pk_mul_f32 v[128:129], v[128:129], s[36:37] op_sel_hi:[1,0]
	v_pk_mul_f32 v[122:123], v[122:123], s[36:37] op_sel_hi:[1,0]
	v_pk_mul_f32 v[124:125], v[124:125], s[36:37] op_sel_hi:[1,0]
	v_cvt_pk_bf16_f32 v140, v126, v127
	v_cvt_pk_bf16_f32 v141, v128, v129
	v_cvt_pk_bf16_f32 v142, v122, v123
	v_cvt_pk_bf16_f32 v143, v124, v125
	v_pk_mul_f32 v[136:137], v[118:119], v[176:177] op_sel:[1,0] op_sel_hi:[0,0]
	v_pk_fma_f32 v[118:119], v[118:119], v[172:173], v[136:137] op_sel:[0,0,0] op_sel_hi:[1,0,1] neg_lo:[0,0,1]
	v_pk_mul_f32 v[136:137], v[120:121], v[176:177] op_sel:[1,1] op_sel_hi:[0,1]
	v_pk_fma_f32 v[120:121], v[120:121], v[172:173], v[136:137] op_sel:[0,1,0] op_sel_hi:[1,1,1] neg_lo:[0,0,1]
	v_pk_mul_f32 v[136:137], v[114:115], v[178:179] op_sel:[1,0] op_sel_hi:[0,0]
	v_pk_fma_f32 v[114:115], v[114:115], v[174:175], v[136:137] op_sel:[0,0,0] op_sel_hi:[1,0,1] neg_lo:[0,0,1]
	v_pk_mul_f32 v[136:137], v[116:117], v[178:179] op_sel:[1,1] op_sel_hi:[0,1]
	v_pk_fma_f32 v[116:117], v[116:117], v[174:175], v[136:137] op_sel:[0,1,0] op_sel_hi:[1,1,1] neg_lo:[0,0,1]
	v_pk_mul_f32 v[118:119], v[118:119], s[36:37] op_sel_hi:[1,0]
	v_pk_mul_f32 v[120:121], v[120:121], s[36:37] op_sel_hi:[1,0]
	v_pk_mul_f32 v[114:115], v[114:115], s[36:37] op_sel_hi:[1,0]
	v_pk_mul_f32 v[116:117], v[116:117], s[36:37] op_sel_hi:[1,0]
	v_cvt_pk_bf16_f32 v144, v118, v119
	v_cvt_pk_bf16_f32 v145, v120, v121
	v_cvt_pk_bf16_f32 v146, v114, v115
	v_cvt_pk_bf16_f32 v147, v116, v117
	ds_bpermute_b32 v218, v180, v140
	ds_bpermute_b32 v219, v180, v141
	ds_bpermute_b32 v220, v180, v142
	ds_bpermute_b32 v221, v180, v143
	ds_bpermute_b32 v222, v180, v144
	ds_bpermute_b32 v223, v180, v145
	ds_bpermute_b32 v224, v180, v146
	ds_bpermute_b32 v225, v180, v147
	s_add_u32 s8, s8, 0x800
	s_addc_u32 s9, s9, 0
	global_load_dwordx4 v[164:167], v131, s[8:9]
	global_load_dwordx4 v[168:171], v132, s[8:9]
	global_load_dwordx4 v[172:175], v131, s[8:9] offset:64
	global_load_dwordx4 v[176:179], v132, s[8:9] offset:64
	v_mul_f32_e32 v134, v109, v109
	v_fmac_f32_e32 v134, v108, v108
	v_fmac_f32_e32 v134, v110, v110
	v_fmac_f32_e32 v134, v111, v111
	v_fmac_f32_e32 v134, v104, v104
	v_fmac_f32_e32 v134, v105, v105
	v_fmac_f32_e32 v134, v106, v106
	v_fmac_f32_e32 v134, v107, v107
	v_fmac_f32_e32 v134, v100, v100
	v_fmac_f32_e32 v134, v101, v101
	v_pk_mul_f32 v[136:137], v[102:103], v[102:103]
	v_pk_mul_f32 v[138:139], v[96:97], v[96:97]
	v_add_f32_e32 v134, v136, v134
	v_add_f32_e32 v134, v137, v134
	v_add_f32_e32 v134, v138, v134
	v_pk_mul_f32 v[136:137], v[98:99], v[98:99]
	v_add_f32_e32 v134, v139, v134
	v_add_f32_e32 v134, v136, v134
	v_add_f32_e32 v134, v137, v134
	ds_swizzle_b32 v135, v134 offset:swizzle(SWAP,16)
	s_waitcnt lgkmcnt(0)
	v_add_f32_e32 v134, v134, v135
	v_mov_b32_e32 v135, v134
	s_nop 1
	v_permlane32_swap_b32 v134, v135
	s_nop 1
	v_add_f32_e32 v134, v134, v135
	v_fmamk_f32 v134, v134, 0x3c800000, v242
	v_rsq_f32_e32 v134, v134
	s_nop 0
	v_pk_mul_f32 v[136:137], v[134:135], v[148:149] op_sel_hi:[0,1]
	v_pk_mul_f32 v[108:109], v[108:109], v[136:137]
	v_pk_mul_f32 v[136:137], v[134:135], v[150:151] op_sel_hi:[0,1]
	v_pk_mul_f32 v[110:111], v[110:111], v[136:137]
	v_pk_mul_f32 v[136:137], v[134:135], v[152:153] op_sel_hi:[0,1]
	v_pk_mul_f32 v[104:105], v[104:105], v[136:137]
	v_pk_mul_f32 v[136:137], v[134:135], v[154:155] op_sel_hi:[0,1]
	v_pk_mul_f32 v[106:107], v[106:107], v[136:137]
	v_pk_mul_f32 v[136:137], v[134:135], v[156:157] op_sel_hi:[0,1]
	v_pk_mul_f32 v[100:101], v[100:101], v[136:137]
	v_pk_mul_f32 v[136:137], v[134:135], v[158:159] op_sel_hi:[0,1]
	v_pk_mul_f32 v[102:103], v[102:103], v[136:137]
	v_pk_mul_f32 v[136:137], v[134:135], v[160:161] op_sel_hi:[0,1]
	v_pk_mul_f32 v[96:97], v[96:97], v[136:137]
	v_pk_mul_f32 v[136:137], v[134:135], v[162:163] op_sel_hi:[0,1]
	v_pk_mul_f32 v[98:99], v[98:99], v[136:137]
	s_waitcnt vmcnt(4)
	v_pk_mul_f32 v[136:137], v[108:109], v[206:207] op_sel:[1,0] op_sel_hi:[0,0]
	v_pk_fma_f32 v[108:109], v[108:109], v[202:203], v[136:137] op_sel:[0,0,0] op_sel_hi:[1,0,1] neg_lo:[0,0,1]
	v_pk_mul_f32 v[136:137], v[110:111], v[206:207] op_sel:[1,1] op_sel_hi:[0,1]
	v_pk_fma_f32 v[110:111], v[110:111], v[202:203], v[136:137] op_sel:[0,1,0] op_sel_hi:[1,1,1] neg_lo:[0,0,1]
	v_pk_mul_f32 v[136:137], v[104:105], v[208:209] op_sel:[1,0] op_sel_hi:[0,0]
	v_pk_fma_f32 v[104:105], v[104:105], v[204:205], v[136:137] op_sel:[0,0,0] op_sel_hi:[1,0,1] neg_lo:[0,0,1]
	v_pk_mul_f32 v[136:137], v[106:107], v[208:209] op_sel:[1,1] op_sel_hi:[0,1]
	v_pk_fma_f32 v[106:107], v[106:107], v[204:205], v[136:137] op_sel:[0,1,0] op_sel_hi:[1,1,1] neg_lo:[0,0,1]
	v_pk_mul_f32 v[108:109], v[108:109], s[36:37] op_sel_hi:[1,0]
	v_pk_mul_f32 v[110:111], v[110:111], s[36:37] op_sel_hi:[1,0]
	v_pk_mul_f32 v[104:105], v[104:105], s[36:37] op_sel_hi:[1,0]
	v_pk_mul_f32 v[106:107], v[106:107], s[36:37] op_sel_hi:[1,0]
	v_cvt_pk_bf16_f32 v140, v108, v109
	v_cvt_pk_bf16_f32 v141, v110, v111
	v_cvt_pk_bf16_f32 v142, v104, v105
	v_cvt_pk_bf16_f32 v143, v106, v107
	v_pk_mul_f32 v[136:137], v[100:101], v[214:215] op_sel:[1,0] op_sel_hi:[0,0]
	v_pk_fma_f32 v[100:101], v[100:101], v[210:211], v[136:137] op_sel:[0,0,0] op_sel_hi:[1,0,1] neg_lo:[0,0,1]
	v_pk_mul_f32 v[136:137], v[102:103], v[214:215] op_sel:[1,1] op_sel_hi:[0,1]
	v_pk_fma_f32 v[102:103], v[102:103], v[210:211], v[136:137] op_sel:[0,1,0] op_sel_hi:[1,1,1] neg_lo:[0,0,1]
	v_pk_mul_f32 v[136:137], v[96:97], v[216:217] op_sel:[1,0] op_sel_hi:[0,0]
	v_pk_fma_f32 v[96:97], v[96:97], v[212:213], v[136:137] op_sel:[0,0,0] op_sel_hi:[1,0,1] neg_lo:[0,0,1]
	v_pk_mul_f32 v[136:137], v[98:99], v[216:217] op_sel:[1,1] op_sel_hi:[0,1]
	v_pk_fma_f32 v[98:99], v[98:99], v[212:213], v[136:137] op_sel:[0,1,0] op_sel_hi:[1,1,1] neg_lo:[0,0,1]
	v_pk_mul_f32 v[100:101], v[100:101], s[36:37] op_sel_hi:[1,0]
	v_pk_mul_f32 v[102:103], v[102:103], s[36:37] op_sel_hi:[1,0]
	v_pk_mul_f32 v[96:97], v[96:97], s[36:37] op_sel_hi:[1,0]
	v_pk_mul_f32 v[98:99], v[98:99], s[36:37] op_sel_hi:[1,0]
	v_cvt_pk_bf16_f32 v144, v100, v101
	v_cvt_pk_bf16_f32 v145, v102, v103
	v_cvt_pk_bf16_f32 v146, v96, v97
	v_cvt_pk_bf16_f32 v147, v98, v99
	s_waitcnt lgkmcnt(0)
	global_store_dwordx4 v130, v[218:221], s[6:7] sc1
	global_store_dwordx4 v130, v[222:225], s[6:7] offset:64 sc1
	s_add_u32 s6, s6, s33
	s_addc_u32 s7, s7, 0
	ds_bpermute_b32 v226, v180, v140
	ds_bpermute_b32 v227, v180, v141
	ds_bpermute_b32 v228, v180, v142
	ds_bpermute_b32 v229, v180, v143
	ds_bpermute_b32 v230, v180, v144
	ds_bpermute_b32 v231, v180, v145
	ds_bpermute_b32 v232, v180, v146
	ds_bpermute_b32 v233, v180, v147
	s_add_u32 s8, s8, 0x800
	s_addc_u32 s9, s9, 0
	global_load_dwordx4 v[202:205], v131, s[8:9]
	global_load_dwordx4 v[206:209], v132, s[8:9]
	global_load_dwordx4 v[210:213], v131, s[8:9] offset:64
	global_load_dwordx4 v[214:217], v132, s[8:9] offset:64
	v_mul_f32_e32 v134, v93, v93
	v_fmac_f32_e32 v134, v92, v92
	v_fmac_f32_e32 v134, v94, v94
	v_fmac_f32_e32 v134, v95, v95
	v_fmac_f32_e32 v134, v88, v88
	v_fmac_f32_e32 v134, v89, v89
	v_fmac_f32_e32 v134, v90, v90
	v_fmac_f32_e32 v134, v91, v91
	v_fmac_f32_e32 v134, v84, v84
	v_fmac_f32_e32 v134, v85, v85
	v_pk_mul_f32 v[136:137], v[86:87], v[86:87]
	v_pk_mul_f32 v[138:139], v[80:81], v[80:81]
	v_add_f32_e32 v134, v136, v134
	v_add_f32_e32 v134, v137, v134
	v_add_f32_e32 v134, v138, v134
	v_pk_mul_f32 v[136:137], v[82:83], v[82:83]
	v_add_f32_e32 v134, v139, v134
	v_add_f32_e32 v134, v136, v134
	v_add_f32_e32 v134, v137, v134
	ds_swizzle_b32 v135, v134 offset:swizzle(SWAP,16)
	s_waitcnt lgkmcnt(0)
	v_add_f32_e32 v134, v134, v135
	v_mov_b32_e32 v135, v134
	s_nop 1
	v_permlane32_swap_b32 v134, v135
	s_nop 1
	v_add_f32_e32 v134, v134, v135
	v_fmamk_f32 v134, v134, 0x3c800000, v242
	v_rsq_f32_e32 v134, v134
	s_nop 0
	v_pk_mul_f32 v[136:137], v[134:135], v[148:149] op_sel_hi:[0,1]
	v_pk_mul_f32 v[92:93], v[92:93], v[136:137]
	v_pk_mul_f32 v[136:137], v[134:135], v[150:151] op_sel_hi:[0,1]
	v_pk_mul_f32 v[94:95], v[94:95], v[136:137]
	v_pk_mul_f32 v[136:137], v[134:135], v[152:153] op_sel_hi:[0,1]
	v_pk_mul_f32 v[88:89], v[88:89], v[136:137]
	v_pk_mul_f32 v[136:137], v[134:135], v[154:155] op_sel_hi:[0,1]
	v_pk_mul_f32 v[90:91], v[90:91], v[136:137]
	v_pk_mul_f32 v[136:137], v[134:135], v[156:157] op_sel_hi:[0,1]
	v_pk_mul_f32 v[84:85], v[84:85], v[136:137]
	v_pk_mul_f32 v[136:137], v[134:135], v[158:159] op_sel_hi:[0,1]
	v_pk_mul_f32 v[86:87], v[86:87], v[136:137]
	v_pk_mul_f32 v[136:137], v[134:135], v[160:161] op_sel_hi:[0,1]
	v_pk_mul_f32 v[80:81], v[80:81], v[136:137]
	v_pk_mul_f32 v[136:137], v[134:135], v[162:163] op_sel_hi:[0,1]
	v_pk_mul_f32 v[82:83], v[82:83], v[136:137]
	s_waitcnt vmcnt(6)
	v_pk_mul_f32 v[136:137], v[92:93], v[168:169] op_sel:[1,0] op_sel_hi:[0,0]
	v_pk_fma_f32 v[92:93], v[92:93], v[164:165], v[136:137] op_sel:[0,0,0] op_sel_hi:[1,0,1] neg_lo:[0,0,1]
	v_pk_mul_f32 v[136:137], v[94:95], v[168:169] op_sel:[1,1] op_sel_hi:[0,1]
	v_pk_fma_f32 v[94:95], v[94:95], v[164:165], v[136:137] op_sel:[0,1,0] op_sel_hi:[1,1,1] neg_lo:[0,0,1]
	v_pk_mul_f32 v[136:137], v[88:89], v[170:171] op_sel:[1,0] op_sel_hi:[0,0]
	v_pk_fma_f32 v[88:89], v[88:89], v[166:167], v[136:137] op_sel:[0,0,0] op_sel_hi:[1,0,1] neg_lo:[0,0,1]
	v_pk_mul_f32 v[136:137], v[90:91], v[170:171] op_sel:[1,1] op_sel_hi:[0,1]
	v_pk_fma_f32 v[90:91], v[90:91], v[166:167], v[136:137] op_sel:[0,1,0] op_sel_hi:[1,1,1] neg_lo:[0,0,1]
	v_pk_mul_f32 v[92:93], v[92:93], s[36:37] op_sel_hi:[1,0]
	v_pk_mul_f32 v[94:95], v[94:95], s[36:37] op_sel_hi:[1,0]
	v_pk_mul_f32 v[88:89], v[88:89], s[36:37] op_sel_hi:[1,0]
	v_pk_mul_f32 v[90:91], v[90:91], s[36:37] op_sel_hi:[1,0]
	v_cvt_pk_bf16_f32 v140, v92, v93
	v_cvt_pk_bf16_f32 v141, v94, v95
	v_cvt_pk_bf16_f32 v142, v88, v89
	v_cvt_pk_bf16_f32 v143, v90, v91
	v_pk_mul_f32 v[136:137], v[84:85], v[176:177] op_sel:[1,0] op_sel_hi:[0,0]
	v_pk_fma_f32 v[84:85], v[84:85], v[172:173], v[136:137] op_sel:[0,0,0] op_sel_hi:[1,0,1] neg_lo:[0,0,1]
	v_pk_mul_f32 v[136:137], v[86:87], v[176:177] op_sel:[1,1] op_sel_hi:[0,1]
	v_pk_fma_f32 v[86:87], v[86:87], v[172:173], v[136:137] op_sel:[0,1,0] op_sel_hi:[1,1,1] neg_lo:[0,0,1]
	v_pk_mul_f32 v[136:137], v[80:81], v[178:179] op_sel:[1,0] op_sel_hi:[0,0]
	v_pk_fma_f32 v[80:81], v[80:81], v[174:175], v[136:137] op_sel:[0,0,0] op_sel_hi:[1,0,1] neg_lo:[0,0,1]
	v_pk_mul_f32 v[136:137], v[82:83], v[178:179] op_sel:[1,1] op_sel_hi:[0,1]
	v_pk_fma_f32 v[82:83], v[82:83], v[174:175], v[136:137] op_sel:[0,1,0] op_sel_hi:[1,1,1] neg_lo:[0,0,1]
	v_pk_mul_f32 v[84:85], v[84:85], s[36:37] op_sel_hi:[1,0]
	v_pk_mul_f32 v[86:87], v[86:87], s[36:37] op_sel_hi:[1,0]
	v_pk_mul_f32 v[80:81], v[80:81], s[36:37] op_sel_hi:[1,0]
	v_pk_mul_f32 v[82:83], v[82:83], s[36:37] op_sel_hi:[1,0]
	v_cvt_pk_bf16_f32 v144, v84, v85
	v_cvt_pk_bf16_f32 v145, v86, v87
	v_cvt_pk_bf16_f32 v146, v80, v81
	v_cvt_pk_bf16_f32 v147, v82, v83
	s_waitcnt lgkmcnt(0)
	global_store_dwordx4 v130, v[226:229], s[6:7] sc1
	global_store_dwordx4 v130, v[230:233], s[6:7] offset:64 sc1
	s_add_u32 s6, s6, s33
	s_addc_u32 s7, s7, 0
	ds_bpermute_b32 v218, v180, v140
	ds_bpermute_b32 v219, v180, v141
	ds_bpermute_b32 v220, v180, v142
	ds_bpermute_b32 v221, v180, v143
	ds_bpermute_b32 v222, v180, v144
	ds_bpermute_b32 v223, v180, v145
	ds_bpermute_b32 v224, v180, v146
	ds_bpermute_b32 v225, v180, v147
	s_add_u32 s8, s8, 0x2800
	s_addc_u32 s9, s9, 0
	global_load_dwordx4 v[164:167], v131, s[8:9]
	global_load_dwordx4 v[168:171], v132, s[8:9]
	global_load_dwordx4 v[172:175], v131, s[8:9] offset:64
	global_load_dwordx4 v[176:179], v132, s[8:9] offset:64
	v_mul_f32_e32 v134, v77, v77
	v_fmac_f32_e32 v134, v76, v76
	v_fmac_f32_e32 v134, v78, v78
	v_fmac_f32_e32 v134, v79, v79
	v_fmac_f32_e32 v134, v72, v72
	v_fmac_f32_e32 v134, v73, v73
	v_fmac_f32_e32 v134, v74, v74
	v_fmac_f32_e32 v134, v75, v75
	v_fmac_f32_e32 v134, v68, v68
	v_fmac_f32_e32 v134, v69, v69
	v_pk_mul_f32 v[136:137], v[70:71], v[70:71]
	v_pk_mul_f32 v[138:139], v[64:65], v[64:65]
	v_add_f32_e32 v134, v136, v134
	v_add_f32_e32 v134, v137, v134
	v_add_f32_e32 v134, v138, v134
	v_pk_mul_f32 v[136:137], v[66:67], v[66:67]
	v_add_f32_e32 v134, v139, v134
	v_add_f32_e32 v134, v136, v134
	v_add_f32_e32 v134, v137, v134
	ds_swizzle_b32 v135, v134 offset:swizzle(SWAP,16)
	s_waitcnt lgkmcnt(0)
	v_add_f32_e32 v134, v134, v135
	v_mov_b32_e32 v135, v134
	s_nop 1
	v_permlane32_swap_b32 v134, v135
	s_nop 1
	v_add_f32_e32 v134, v134, v135
	v_fmamk_f32 v134, v134, 0x3c800000, v242
	v_rsq_f32_e32 v134, v134
	s_nop 0
	v_pk_mul_f32 v[136:137], v[134:135], v[148:149] op_sel_hi:[0,1]
	v_pk_mul_f32 v[76:77], v[76:77], v[136:137]
	v_pk_mul_f32 v[136:137], v[134:135], v[150:151] op_sel_hi:[0,1]
	v_pk_mul_f32 v[78:79], v[78:79], v[136:137]
	v_pk_mul_f32 v[136:137], v[134:135], v[152:153] op_sel_hi:[0,1]
	v_pk_mul_f32 v[72:73], v[72:73], v[136:137]
	v_pk_mul_f32 v[136:137], v[134:135], v[154:155] op_sel_hi:[0,1]
	v_pk_mul_f32 v[74:75], v[74:75], v[136:137]
	v_pk_mul_f32 v[136:137], v[134:135], v[156:157] op_sel_hi:[0,1]
	v_pk_mul_f32 v[68:69], v[68:69], v[136:137]
	v_pk_mul_f32 v[136:137], v[134:135], v[158:159] op_sel_hi:[0,1]
	v_pk_mul_f32 v[70:71], v[70:71], v[136:137]
	v_pk_mul_f32 v[136:137], v[134:135], v[160:161] op_sel_hi:[0,1]
	v_pk_mul_f32 v[64:65], v[64:65], v[136:137]
	v_pk_mul_f32 v[136:137], v[134:135], v[162:163] op_sel_hi:[0,1]
	v_pk_mul_f32 v[66:67], v[66:67], v[136:137]
	s_waitcnt vmcnt(6)
	v_pk_mul_f32 v[136:137], v[76:77], v[206:207] op_sel:[1,0] op_sel_hi:[0,0]
	v_pk_fma_f32 v[76:77], v[76:77], v[202:203], v[136:137] op_sel:[0,0,0] op_sel_hi:[1,0,1] neg_lo:[0,0,1]
	v_pk_mul_f32 v[136:137], v[78:79], v[206:207] op_sel:[1,1] op_sel_hi:[0,1]
	v_pk_fma_f32 v[78:79], v[78:79], v[202:203], v[136:137] op_sel:[0,1,0] op_sel_hi:[1,1,1] neg_lo:[0,0,1]
	v_pk_mul_f32 v[136:137], v[72:73], v[208:209] op_sel:[1,0] op_sel_hi:[0,0]
	v_pk_fma_f32 v[72:73], v[72:73], v[204:205], v[136:137] op_sel:[0,0,0] op_sel_hi:[1,0,1] neg_lo:[0,0,1]
	v_pk_mul_f32 v[136:137], v[74:75], v[208:209] op_sel:[1,1] op_sel_hi:[0,1]
	v_pk_fma_f32 v[74:75], v[74:75], v[204:205], v[136:137] op_sel:[0,1,0] op_sel_hi:[1,1,1] neg_lo:[0,0,1]
	v_pk_mul_f32 v[76:77], v[76:77], s[36:37] op_sel_hi:[1,0]
	v_pk_mul_f32 v[78:79], v[78:79], s[36:37] op_sel_hi:[1,0]
	v_pk_mul_f32 v[72:73], v[72:73], s[36:37] op_sel_hi:[1,0]
	v_pk_mul_f32 v[74:75], v[74:75], s[36:37] op_sel_hi:[1,0]
	v_cvt_pk_bf16_f32 v140, v76, v77
	v_cvt_pk_bf16_f32 v141, v78, v79
	v_cvt_pk_bf16_f32 v142, v72, v73
	v_cvt_pk_bf16_f32 v143, v74, v75
	v_pk_mul_f32 v[136:137], v[68:69], v[214:215] op_sel:[1,0] op_sel_hi:[0,0]
	v_pk_fma_f32 v[68:69], v[68:69], v[210:211], v[136:137] op_sel:[0,0,0] op_sel_hi:[1,0,1] neg_lo:[0,0,1]
	v_pk_mul_f32 v[136:137], v[70:71], v[214:215] op_sel:[1,1] op_sel_hi:[0,1]
	v_pk_fma_f32 v[70:71], v[70:71], v[210:211], v[136:137] op_sel:[0,1,0] op_sel_hi:[1,1,1] neg_lo:[0,0,1]
	v_pk_mul_f32 v[136:137], v[64:65], v[216:217] op_sel:[1,0] op_sel_hi:[0,0]
	v_pk_fma_f32 v[64:65], v[64:65], v[212:213], v[136:137] op_sel:[0,0,0] op_sel_hi:[1,0,1] neg_lo:[0,0,1]
	v_pk_mul_f32 v[136:137], v[66:67], v[216:217] op_sel:[1,1] op_sel_hi:[0,1]
	v_pk_fma_f32 v[66:67], v[66:67], v[212:213], v[136:137] op_sel:[0,1,0] op_sel_hi:[1,1,1] neg_lo:[0,0,1]
	v_pk_mul_f32 v[68:69], v[68:69], s[36:37] op_sel_hi:[1,0]
	v_pk_mul_f32 v[70:71], v[70:71], s[36:37] op_sel_hi:[1,0]
	v_pk_mul_f32 v[64:65], v[64:65], s[36:37] op_sel_hi:[1,0]
	v_pk_mul_f32 v[66:67], v[66:67], s[36:37] op_sel_hi:[1,0]
	v_cvt_pk_bf16_f32 v144, v68, v69
	v_cvt_pk_bf16_f32 v145, v70, v71
	v_cvt_pk_bf16_f32 v146, v64, v65
	v_cvt_pk_bf16_f32 v147, v66, v67
	s_waitcnt lgkmcnt(0)
	global_store_dwordx4 v130, v[218:221], s[6:7] sc1
	global_store_dwordx4 v130, v[222:225], s[6:7] offset:64 sc1
	s_add_u32 s6, s6, s33
	s_addc_u32 s7, s7, 0
	ds_bpermute_b32 v226, v180, v140
	ds_bpermute_b32 v227, v180, v141
	ds_bpermute_b32 v228, v180, v142
	ds_bpermute_b32 v229, v180, v143
	ds_bpermute_b32 v230, v180, v144
	ds_bpermute_b32 v231, v180, v145
	ds_bpermute_b32 v232, v180, v146
	ds_bpermute_b32 v233, v180, v147
	s_add_u32 s8, s8, 0x800
	s_addc_u32 s9, s9, 0
	global_load_dwordx4 v[202:205], v131, s[8:9]
	global_load_dwordx4 v[206:209], v132, s[8:9]
	global_load_dwordx4 v[210:213], v131, s[8:9] offset:64
	global_load_dwordx4 v[214:217], v132, s[8:9] offset:64
	v_mul_f32_e32 v134, v61, v61
	v_fmac_f32_e32 v134, v60, v60
	v_fmac_f32_e32 v134, v62, v62
	v_fmac_f32_e32 v134, v63, v63
	v_fmac_f32_e32 v134, v56, v56
	v_fmac_f32_e32 v134, v57, v57
	v_fmac_f32_e32 v134, v58, v58
	v_fmac_f32_e32 v134, v59, v59
	v_fmac_f32_e32 v134, v52, v52
	v_fmac_f32_e32 v134, v53, v53
	v_pk_mul_f32 v[136:137], v[54:55], v[54:55]
	v_pk_mul_f32 v[138:139], v[48:49], v[48:49]
	v_add_f32_e32 v134, v136, v134
	v_add_f32_e32 v134, v137, v134
	v_add_f32_e32 v134, v138, v134
	v_pk_mul_f32 v[136:137], v[50:51], v[50:51]
	v_add_f32_e32 v134, v139, v134
	v_add_f32_e32 v134, v136, v134
	v_add_f32_e32 v134, v137, v134
	ds_swizzle_b32 v135, v134 offset:swizzle(SWAP,16)
	s_waitcnt lgkmcnt(0)
	v_add_f32_e32 v134, v134, v135
	v_mov_b32_e32 v135, v134
	s_nop 1
	v_permlane32_swap_b32 v134, v135
	s_nop 1
	v_add_f32_e32 v134, v134, v135
	v_fmamk_f32 v134, v134, 0x3c800000, v242
	v_rsq_f32_e32 v134, v134
	s_nop 0
	v_pk_mul_f32 v[136:137], v[134:135], v[148:149] op_sel_hi:[0,1]
	v_pk_mul_f32 v[60:61], v[60:61], v[136:137]
	v_pk_mul_f32 v[136:137], v[134:135], v[150:151] op_sel_hi:[0,1]
	v_pk_mul_f32 v[62:63], v[62:63], v[136:137]
	v_pk_mul_f32 v[136:137], v[134:135], v[152:153] op_sel_hi:[0,1]
	v_pk_mul_f32 v[56:57], v[56:57], v[136:137]
	v_pk_mul_f32 v[136:137], v[134:135], v[154:155] op_sel_hi:[0,1]
	v_pk_mul_f32 v[58:59], v[58:59], v[136:137]
	v_pk_mul_f32 v[136:137], v[134:135], v[156:157] op_sel_hi:[0,1]
	v_pk_mul_f32 v[52:53], v[52:53], v[136:137]
	v_pk_mul_f32 v[136:137], v[134:135], v[158:159] op_sel_hi:[0,1]
	v_pk_mul_f32 v[54:55], v[54:55], v[136:137]
	v_pk_mul_f32 v[136:137], v[134:135], v[160:161] op_sel_hi:[0,1]
	v_pk_mul_f32 v[48:49], v[48:49], v[136:137]
	v_pk_mul_f32 v[136:137], v[134:135], v[162:163] op_sel_hi:[0,1]
	v_pk_mul_f32 v[50:51], v[50:51], v[136:137]
	s_waitcnt vmcnt(6)
	v_pk_mul_f32 v[136:137], v[60:61], v[168:169] op_sel:[1,0] op_sel_hi:[0,0]
	v_pk_fma_f32 v[60:61], v[60:61], v[164:165], v[136:137] op_sel:[0,0,0] op_sel_hi:[1,0,1] neg_lo:[0,0,1]
	v_pk_mul_f32 v[136:137], v[62:63], v[168:169] op_sel:[1,1] op_sel_hi:[0,1]
	v_pk_fma_f32 v[62:63], v[62:63], v[164:165], v[136:137] op_sel:[0,1,0] op_sel_hi:[1,1,1] neg_lo:[0,0,1]
	v_pk_mul_f32 v[136:137], v[56:57], v[170:171] op_sel:[1,0] op_sel_hi:[0,0]
	v_pk_fma_f32 v[56:57], v[56:57], v[166:167], v[136:137] op_sel:[0,0,0] op_sel_hi:[1,0,1] neg_lo:[0,0,1]
	v_pk_mul_f32 v[136:137], v[58:59], v[170:171] op_sel:[1,1] op_sel_hi:[0,1]
	v_pk_fma_f32 v[58:59], v[58:59], v[166:167], v[136:137] op_sel:[0,1,0] op_sel_hi:[1,1,1] neg_lo:[0,0,1]
	v_pk_mul_f32 v[60:61], v[60:61], s[36:37] op_sel_hi:[1,0]
	v_pk_mul_f32 v[62:63], v[62:63], s[36:37] op_sel_hi:[1,0]
	v_pk_mul_f32 v[56:57], v[56:57], s[36:37] op_sel_hi:[1,0]
	v_pk_mul_f32 v[58:59], v[58:59], s[36:37] op_sel_hi:[1,0]
	v_cvt_pk_bf16_f32 v140, v60, v61
	v_cvt_pk_bf16_f32 v141, v62, v63
	v_cvt_pk_bf16_f32 v142, v56, v57
	v_cvt_pk_bf16_f32 v143, v58, v59
	v_pk_mul_f32 v[136:137], v[52:53], v[176:177] op_sel:[1,0] op_sel_hi:[0,0]
	v_pk_fma_f32 v[52:53], v[52:53], v[172:173], v[136:137] op_sel:[0,0,0] op_sel_hi:[1,0,1] neg_lo:[0,0,1]
	v_pk_mul_f32 v[136:137], v[54:55], v[176:177] op_sel:[1,1] op_sel_hi:[0,1]
	v_pk_fma_f32 v[54:55], v[54:55], v[172:173], v[136:137] op_sel:[0,1,0] op_sel_hi:[1,1,1] neg_lo:[0,0,1]
	v_pk_mul_f32 v[136:137], v[48:49], v[178:179] op_sel:[1,0] op_sel_hi:[0,0]
	v_pk_fma_f32 v[48:49], v[48:49], v[174:175], v[136:137] op_sel:[0,0,0] op_sel_hi:[1,0,1] neg_lo:[0,0,1]
	v_pk_mul_f32 v[136:137], v[50:51], v[178:179] op_sel:[1,1] op_sel_hi:[0,1]
	v_pk_fma_f32 v[50:51], v[50:51], v[174:175], v[136:137] op_sel:[0,1,0] op_sel_hi:[1,1,1] neg_lo:[0,0,1]
	v_pk_mul_f32 v[52:53], v[52:53], s[36:37] op_sel_hi:[1,0]
	v_pk_mul_f32 v[54:55], v[54:55], s[36:37] op_sel_hi:[1,0]
	v_pk_mul_f32 v[48:49], v[48:49], s[36:37] op_sel_hi:[1,0]
	v_pk_mul_f32 v[50:51], v[50:51], s[36:37] op_sel_hi:[1,0]
	v_cvt_pk_bf16_f32 v144, v52, v53
	v_cvt_pk_bf16_f32 v145, v54, v55
	v_cvt_pk_bf16_f32 v146, v48, v49
	v_cvt_pk_bf16_f32 v147, v50, v51
	s_waitcnt lgkmcnt(0)
	global_store_dwordx4 v130, v[226:229], s[6:7] sc1
	global_store_dwordx4 v130, v[230:233], s[6:7] offset:64 sc1
	s_add_u32 s6, s6, s34
	s_addc_u32 s7, s7, 0
	ds_bpermute_b32 v218, v180, v140
	ds_bpermute_b32 v219, v180, v141
	ds_bpermute_b32 v220, v180, v142
	ds_bpermute_b32 v221, v180, v143
	ds_bpermute_b32 v222, v180, v144
	ds_bpermute_b32 v223, v180, v145
	ds_bpermute_b32 v224, v180, v146
	ds_bpermute_b32 v225, v180, v147
	s_add_u32 s8, s8, 0x800
	s_addc_u32 s9, s9, 0
	global_load_dwordx4 v[164:167], v131, s[8:9]
	global_load_dwordx4 v[168:171], v132, s[8:9]
	global_load_dwordx4 v[172:175], v131, s[8:9] offset:64
	global_load_dwordx4 v[176:179], v132, s[8:9] offset:64
	v_mul_f32_e32 v134, v45, v45
	v_fmac_f32_e32 v134, v44, v44
	v_fmac_f32_e32 v134, v46, v46
	v_fmac_f32_e32 v134, v47, v47
	v_fmac_f32_e32 v134, v40, v40
	v_fmac_f32_e32 v134, v41, v41
	v_fmac_f32_e32 v134, v42, v42
	v_fmac_f32_e32 v134, v43, v43
	v_fmac_f32_e32 v134, v36, v36
	v_fmac_f32_e32 v134, v37, v37
	v_pk_mul_f32 v[136:137], v[38:39], v[38:39]
	v_pk_mul_f32 v[138:139], v[32:33], v[32:33]
	v_add_f32_e32 v134, v136, v134
	v_add_f32_e32 v134, v137, v134
	v_add_f32_e32 v134, v138, v134
	v_pk_mul_f32 v[136:137], v[34:35], v[34:35]
	v_add_f32_e32 v134, v139, v134
	v_add_f32_e32 v134, v136, v134
	v_add_f32_e32 v134, v137, v134
	ds_swizzle_b32 v135, v134 offset:swizzle(SWAP,16)
	s_waitcnt lgkmcnt(0)
	v_add_f32_e32 v134, v134, v135
	v_mov_b32_e32 v135, v134
	s_nop 1
	v_permlane32_swap_b32 v134, v135
	s_nop 1
	v_add_f32_e32 v134, v134, v135
	v_fmamk_f32 v134, v134, 0x3c800000, v242
	v_rsq_f32_e32 v134, v134
	s_nop 0
	v_pk_mul_f32 v[136:137], v[134:135], v[148:149] op_sel_hi:[0,1]
	v_pk_mul_f32 v[44:45], v[44:45], v[136:137]
	v_pk_mul_f32 v[136:137], v[134:135], v[150:151] op_sel_hi:[0,1]
	v_pk_mul_f32 v[46:47], v[46:47], v[136:137]
	v_pk_mul_f32 v[136:137], v[134:135], v[152:153] op_sel_hi:[0,1]
	v_pk_mul_f32 v[40:41], v[40:41], v[136:137]
	v_pk_mul_f32 v[136:137], v[134:135], v[154:155] op_sel_hi:[0,1]
	v_pk_mul_f32 v[42:43], v[42:43], v[136:137]
	v_pk_mul_f32 v[136:137], v[134:135], v[156:157] op_sel_hi:[0,1]
	v_pk_mul_f32 v[36:37], v[36:37], v[136:137]
	v_pk_mul_f32 v[136:137], v[134:135], v[158:159] op_sel_hi:[0,1]
	v_pk_mul_f32 v[38:39], v[38:39], v[136:137]
	v_pk_mul_f32 v[136:137], v[134:135], v[160:161] op_sel_hi:[0,1]
	v_pk_mul_f32 v[32:33], v[32:33], v[136:137]
	v_pk_mul_f32 v[136:137], v[134:135], v[162:163] op_sel_hi:[0,1]
	v_pk_mul_f32 v[34:35], v[34:35], v[136:137]
	s_waitcnt vmcnt(6)
	v_pk_mul_f32 v[136:137], v[44:45], v[206:207] op_sel:[1,0] op_sel_hi:[0,0]
	v_pk_fma_f32 v[44:45], v[44:45], v[202:203], v[136:137] op_sel:[0,0,0] op_sel_hi:[1,0,1] neg_lo:[0,0,1]
	v_pk_mul_f32 v[136:137], v[46:47], v[206:207] op_sel:[1,1] op_sel_hi:[0,1]
	v_pk_fma_f32 v[46:47], v[46:47], v[202:203], v[136:137] op_sel:[0,1,0] op_sel_hi:[1,1,1] neg_lo:[0,0,1]
	v_pk_mul_f32 v[136:137], v[40:41], v[208:209] op_sel:[1,0] op_sel_hi:[0,0]
	v_pk_fma_f32 v[40:41], v[40:41], v[204:205], v[136:137] op_sel:[0,0,0] op_sel_hi:[1,0,1] neg_lo:[0,0,1]
	v_pk_mul_f32 v[136:137], v[42:43], v[208:209] op_sel:[1,1] op_sel_hi:[0,1]
	v_pk_fma_f32 v[42:43], v[42:43], v[204:205], v[136:137] op_sel:[0,1,0] op_sel_hi:[1,1,1] neg_lo:[0,0,1]
	v_pk_mul_f32 v[44:45], v[44:45], s[36:37] op_sel_hi:[1,0]
	v_pk_mul_f32 v[46:47], v[46:47], s[36:37] op_sel_hi:[1,0]
	v_pk_mul_f32 v[40:41], v[40:41], s[36:37] op_sel_hi:[1,0]
	v_pk_mul_f32 v[42:43], v[42:43], s[36:37] op_sel_hi:[1,0]
	v_cvt_pk_bf16_f32 v140, v44, v45
	v_cvt_pk_bf16_f32 v141, v46, v47
	v_cvt_pk_bf16_f32 v142, v40, v41
	v_cvt_pk_bf16_f32 v143, v42, v43
	v_pk_mul_f32 v[136:137], v[36:37], v[214:215] op_sel:[1,0] op_sel_hi:[0,0]
	v_pk_fma_f32 v[36:37], v[36:37], v[210:211], v[136:137] op_sel:[0,0,0] op_sel_hi:[1,0,1] neg_lo:[0,0,1]
	v_pk_mul_f32 v[136:137], v[38:39], v[214:215] op_sel:[1,1] op_sel_hi:[0,1]
	v_pk_fma_f32 v[38:39], v[38:39], v[210:211], v[136:137] op_sel:[0,1,0] op_sel_hi:[1,1,1] neg_lo:[0,0,1]
	v_pk_mul_f32 v[136:137], v[32:33], v[216:217] op_sel:[1,0] op_sel_hi:[0,0]
	v_pk_fma_f32 v[32:33], v[32:33], v[212:213], v[136:137] op_sel:[0,0,0] op_sel_hi:[1,0,1] neg_lo:[0,0,1]
	v_pk_mul_f32 v[136:137], v[34:35], v[216:217] op_sel:[1,1] op_sel_hi:[0,1]
	v_pk_fma_f32 v[34:35], v[34:35], v[212:213], v[136:137] op_sel:[0,1,0] op_sel_hi:[1,1,1] neg_lo:[0,0,1]
	v_pk_mul_f32 v[36:37], v[36:37], s[36:37] op_sel_hi:[1,0]
	v_pk_mul_f32 v[38:39], v[38:39], s[36:37] op_sel_hi:[1,0]
	v_pk_mul_f32 v[32:33], v[32:33], s[36:37] op_sel_hi:[1,0]
	v_pk_mul_f32 v[34:35], v[34:35], s[36:37] op_sel_hi:[1,0]
	v_cvt_pk_bf16_f32 v144, v36, v37
	v_cvt_pk_bf16_f32 v145, v38, v39
	v_cvt_pk_bf16_f32 v146, v32, v33
	v_cvt_pk_bf16_f32 v147, v34, v35
	s_waitcnt lgkmcnt(0)
	global_store_dwordx4 v130, v[218:221], s[6:7] sc1
	global_store_dwordx4 v130, v[222:225], s[6:7] offset:64 sc1
	s_add_u32 s6, s6, s33
	s_addc_u32 s7, s7, 0
	ds_bpermute_b32 v226, v180, v140
	ds_bpermute_b32 v227, v180, v141
	ds_bpermute_b32 v228, v180, v142
	ds_bpermute_b32 v229, v180, v143
	ds_bpermute_b32 v230, v180, v144
	ds_bpermute_b32 v231, v180, v145
	ds_bpermute_b32 v232, v180, v146
	ds_bpermute_b32 v233, v180, v147
	s_add_u32 s8, s8, 0x800
	s_addc_u32 s9, s9, 0
	global_load_dwordx4 v[202:205], v131, s[8:9]
	global_load_dwordx4 v[206:209], v132, s[8:9]
	global_load_dwordx4 v[210:213], v131, s[8:9] offset:64
	global_load_dwordx4 v[214:217], v132, s[8:9] offset:64
	v_mul_f32_e32 v134, v29, v29
	v_fmac_f32_e32 v134, v28, v28
	v_fmac_f32_e32 v134, v30, v30
	v_fmac_f32_e32 v134, v31, v31
	v_fmac_f32_e32 v134, v24, v24
	v_fmac_f32_e32 v134, v25, v25
	v_fmac_f32_e32 v134, v26, v26
	v_fmac_f32_e32 v134, v27, v27
	v_fmac_f32_e32 v134, v20, v20
	v_fmac_f32_e32 v134, v21, v21
	v_pk_mul_f32 v[136:137], v[22:23], v[22:23]
	v_pk_mul_f32 v[138:139], v[16:17], v[16:17]
	v_add_f32_e32 v134, v136, v134
	v_add_f32_e32 v134, v137, v134
	v_add_f32_e32 v134, v138, v134
	v_pk_mul_f32 v[136:137], v[18:19], v[18:19]
	v_add_f32_e32 v134, v139, v134
	v_add_f32_e32 v134, v136, v134
	v_add_f32_e32 v134, v137, v134
	ds_swizzle_b32 v135, v134 offset:swizzle(SWAP,16)
	s_waitcnt lgkmcnt(0)
	v_add_f32_e32 v134, v134, v135
	v_mov_b32_e32 v135, v134
	s_nop 1
	v_permlane32_swap_b32 v134, v135
	s_nop 1
	v_add_f32_e32 v134, v134, v135
	v_fmamk_f32 v134, v134, 0x3c800000, v242
	v_rsq_f32_e32 v134, v134
	s_nop 0
	v_pk_mul_f32 v[136:137], v[134:135], v[148:149] op_sel_hi:[0,1]
	v_pk_mul_f32 v[28:29], v[28:29], v[136:137]
	v_pk_mul_f32 v[136:137], v[134:135], v[150:151] op_sel_hi:[0,1]
	v_pk_mul_f32 v[30:31], v[30:31], v[136:137]
	v_pk_mul_f32 v[136:137], v[134:135], v[152:153] op_sel_hi:[0,1]
	v_pk_mul_f32 v[24:25], v[24:25], v[136:137]
	v_pk_mul_f32 v[136:137], v[134:135], v[154:155] op_sel_hi:[0,1]
	v_pk_mul_f32 v[26:27], v[26:27], v[136:137]
	v_pk_mul_f32 v[136:137], v[134:135], v[156:157] op_sel_hi:[0,1]
	v_pk_mul_f32 v[20:21], v[20:21], v[136:137]
	v_pk_mul_f32 v[136:137], v[134:135], v[158:159] op_sel_hi:[0,1]
	v_pk_mul_f32 v[22:23], v[22:23], v[136:137]
	v_pk_mul_f32 v[136:137], v[134:135], v[160:161] op_sel_hi:[0,1]
	v_pk_mul_f32 v[16:17], v[16:17], v[136:137]
	v_pk_mul_f32 v[136:137], v[134:135], v[162:163] op_sel_hi:[0,1]
	v_pk_mul_f32 v[18:19], v[18:19], v[136:137]
	s_waitcnt vmcnt(6)
	v_pk_mul_f32 v[136:137], v[28:29], v[168:169] op_sel:[1,0] op_sel_hi:[0,0]
	v_pk_fma_f32 v[28:29], v[28:29], v[164:165], v[136:137] op_sel:[0,0,0] op_sel_hi:[1,0,1] neg_lo:[0,0,1]
	v_pk_mul_f32 v[136:137], v[30:31], v[168:169] op_sel:[1,1] op_sel_hi:[0,1]
	v_pk_fma_f32 v[30:31], v[30:31], v[164:165], v[136:137] op_sel:[0,1,0] op_sel_hi:[1,1,1] neg_lo:[0,0,1]
	v_pk_mul_f32 v[136:137], v[24:25], v[170:171] op_sel:[1,0] op_sel_hi:[0,0]
	v_pk_fma_f32 v[24:25], v[24:25], v[166:167], v[136:137] op_sel:[0,0,0] op_sel_hi:[1,0,1] neg_lo:[0,0,1]
	v_pk_mul_f32 v[136:137], v[26:27], v[170:171] op_sel:[1,1] op_sel_hi:[0,1]
	v_pk_fma_f32 v[26:27], v[26:27], v[166:167], v[136:137] op_sel:[0,1,0] op_sel_hi:[1,1,1] neg_lo:[0,0,1]
	v_pk_mul_f32 v[28:29], v[28:29], s[36:37] op_sel_hi:[1,0]
	v_pk_mul_f32 v[30:31], v[30:31], s[36:37] op_sel_hi:[1,0]
	v_pk_mul_f32 v[24:25], v[24:25], s[36:37] op_sel_hi:[1,0]
	v_pk_mul_f32 v[26:27], v[26:27], s[36:37] op_sel_hi:[1,0]
	v_cvt_pk_bf16_f32 v140, v28, v29
	v_cvt_pk_bf16_f32 v141, v30, v31
	v_cvt_pk_bf16_f32 v142, v24, v25
	v_cvt_pk_bf16_f32 v143, v26, v27
	v_pk_mul_f32 v[136:137], v[20:21], v[176:177] op_sel:[1,0] op_sel_hi:[0,0]
	v_pk_fma_f32 v[20:21], v[20:21], v[172:173], v[136:137] op_sel:[0,0,0] op_sel_hi:[1,0,1] neg_lo:[0,0,1]
	v_pk_mul_f32 v[136:137], v[22:23], v[176:177] op_sel:[1,1] op_sel_hi:[0,1]
	v_pk_fma_f32 v[22:23], v[22:23], v[172:173], v[136:137] op_sel:[0,1,0] op_sel_hi:[1,1,1] neg_lo:[0,0,1]
	v_pk_mul_f32 v[136:137], v[16:17], v[178:179] op_sel:[1,0] op_sel_hi:[0,0]
	v_pk_fma_f32 v[16:17], v[16:17], v[174:175], v[136:137] op_sel:[0,0,0] op_sel_hi:[1,0,1] neg_lo:[0,0,1]
	v_pk_mul_f32 v[136:137], v[18:19], v[178:179] op_sel:[1,1] op_sel_hi:[0,1]
	v_pk_fma_f32 v[18:19], v[18:19], v[174:175], v[136:137] op_sel:[0,1,0] op_sel_hi:[1,1,1] neg_lo:[0,0,1]
	v_pk_mul_f32 v[20:21], v[20:21], s[36:37] op_sel_hi:[1,0]
	v_pk_mul_f32 v[22:23], v[22:23], s[36:37] op_sel_hi:[1,0]
	v_pk_mul_f32 v[16:17], v[16:17], s[36:37] op_sel_hi:[1,0]
	v_pk_mul_f32 v[18:19], v[18:19], s[36:37] op_sel_hi:[1,0]
	v_cvt_pk_bf16_f32 v144, v20, v21
	v_cvt_pk_bf16_f32 v145, v22, v23
	v_cvt_pk_bf16_f32 v146, v16, v17
	v_cvt_pk_bf16_f32 v147, v18, v19
	s_waitcnt lgkmcnt(0)
	global_store_dwordx4 v130, v[226:229], s[6:7] sc1
	global_store_dwordx4 v130, v[230:233], s[6:7] offset:64 sc1
	s_add_u32 s6, s6, s33
	s_addc_u32 s7, s7, 0
	ds_bpermute_b32 v218, v180, v140
	ds_bpermute_b32 v219, v180, v141
	ds_bpermute_b32 v220, v180, v142
	ds_bpermute_b32 v221, v180, v143
	ds_bpermute_b32 v222, v180, v144
	ds_bpermute_b32 v223, v180, v145
	ds_bpermute_b32 v224, v180, v146
	ds_bpermute_b32 v225, v180, v147
	v_mul_f32_e32 v134, v13, v13
	v_fmac_f32_e32 v134, v12, v12
	v_fmac_f32_e32 v134, v14, v14
	v_fmac_f32_e32 v134, v15, v15
	v_fmac_f32_e32 v134, v4, v4
	v_fmac_f32_e32 v134, v5, v5
	v_fmac_f32_e32 v134, v6, v6
	v_fmac_f32_e32 v134, v7, v7
	v_fmac_f32_e32 v134, v8, v8
	v_fmac_f32_e32 v134, v9, v9
	v_pk_mul_f32 v[136:137], v[10:11], v[10:11]
	v_pk_mul_f32 v[138:139], v[0:1], v[0:1]
	v_add_f32_e32 v134, v136, v134
	v_add_f32_e32 v134, v137, v134
	v_add_f32_e32 v134, v138, v134
	v_pk_mul_f32 v[136:137], v[2:3], v[2:3]
	v_add_f32_e32 v134, v139, v134
	v_add_f32_e32 v134, v136, v134
	v_add_f32_e32 v134, v137, v134
	ds_swizzle_b32 v135, v134 offset:swizzle(SWAP,16)
	s_waitcnt lgkmcnt(0)
	v_add_f32_e32 v134, v134, v135
	v_mov_b32_e32 v135, v134
	s_nop 1
	v_permlane32_swap_b32 v134, v135
	s_nop 1
	v_add_f32_e32 v134, v134, v135
	v_fmamk_f32 v134, v134, 0x3c800000, v242
	v_rsq_f32_e32 v134, v134
	s_nop 0
	v_pk_mul_f32 v[136:137], v[134:135], v[148:149] op_sel_hi:[0,1]
	v_pk_mul_f32 v[12:13], v[12:13], v[136:137]
	v_pk_mul_f32 v[136:137], v[134:135], v[150:151] op_sel_hi:[0,1]
	v_pk_mul_f32 v[14:15], v[14:15], v[136:137]
	v_pk_mul_f32 v[136:137], v[134:135], v[152:153] op_sel_hi:[0,1]
	v_pk_mul_f32 v[4:5], v[4:5], v[136:137]
	v_pk_mul_f32 v[136:137], v[134:135], v[154:155] op_sel_hi:[0,1]
	v_pk_mul_f32 v[6:7], v[6:7], v[136:137]
	v_pk_mul_f32 v[136:137], v[134:135], v[156:157] op_sel_hi:[0,1]
	v_pk_mul_f32 v[8:9], v[8:9], v[136:137]
	v_pk_mul_f32 v[136:137], v[134:135], v[158:159] op_sel_hi:[0,1]
	v_pk_mul_f32 v[10:11], v[10:11], v[136:137]
	v_pk_mul_f32 v[136:137], v[134:135], v[160:161] op_sel_hi:[0,1]
	v_pk_mul_f32 v[0:1], v[0:1], v[136:137]
	v_pk_mul_f32 v[136:137], v[134:135], v[162:163] op_sel_hi:[0,1]
	v_pk_mul_f32 v[2:3], v[2:3], v[136:137]
	s_waitcnt vmcnt(2)
	v_pk_mul_f32 v[136:137], v[12:13], v[206:207] op_sel:[1,0] op_sel_hi:[0,0]
	v_pk_fma_f32 v[12:13], v[12:13], v[202:203], v[136:137] op_sel:[0,0,0] op_sel_hi:[1,0,1] neg_lo:[0,0,1]
	v_pk_mul_f32 v[136:137], v[14:15], v[206:207] op_sel:[1,1] op_sel_hi:[0,1]
	v_pk_fma_f32 v[14:15], v[14:15], v[202:203], v[136:137] op_sel:[0,1,0] op_sel_hi:[1,1,1] neg_lo:[0,0,1]
	v_pk_mul_f32 v[136:137], v[4:5], v[208:209] op_sel:[1,0] op_sel_hi:[0,0]
	v_pk_fma_f32 v[4:5], v[4:5], v[204:205], v[136:137] op_sel:[0,0,0] op_sel_hi:[1,0,1] neg_lo:[0,0,1]
	v_pk_mul_f32 v[136:137], v[6:7], v[208:209] op_sel:[1,1] op_sel_hi:[0,1]
	v_pk_fma_f32 v[6:7], v[6:7], v[204:205], v[136:137] op_sel:[0,1,0] op_sel_hi:[1,1,1] neg_lo:[0,0,1]
	v_pk_mul_f32 v[12:13], v[12:13], s[36:37] op_sel_hi:[1,0]
	v_pk_mul_f32 v[14:15], v[14:15], s[36:37] op_sel_hi:[1,0]
	v_pk_mul_f32 v[4:5], v[4:5], s[36:37] op_sel_hi:[1,0]
	v_pk_mul_f32 v[6:7], v[6:7], s[36:37] op_sel_hi:[1,0]
	v_cvt_pk_bf16_f32 v140, v12, v13
	v_cvt_pk_bf16_f32 v141, v14, v15
	v_cvt_pk_bf16_f32 v142, v4, v5
	v_cvt_pk_bf16_f32 v143, v6, v7
	v_pk_mul_f32 v[136:137], v[8:9], v[214:215] op_sel:[1,0] op_sel_hi:[0,0]
	v_pk_fma_f32 v[8:9], v[8:9], v[210:211], v[136:137] op_sel:[0,0,0] op_sel_hi:[1,0,1] neg_lo:[0,0,1]
	v_pk_mul_f32 v[136:137], v[10:11], v[214:215] op_sel:[1,1] op_sel_hi:[0,1]
	v_pk_fma_f32 v[10:11], v[10:11], v[210:211], v[136:137] op_sel:[0,1,0] op_sel_hi:[1,1,1] neg_lo:[0,0,1]
	v_pk_mul_f32 v[136:137], v[0:1], v[216:217] op_sel:[1,0] op_sel_hi:[0,0]
	v_pk_fma_f32 v[0:1], v[0:1], v[212:213], v[136:137] op_sel:[0,0,0] op_sel_hi:[1,0,1] neg_lo:[0,0,1]
	v_pk_mul_f32 v[136:137], v[2:3], v[216:217] op_sel:[1,1] op_sel_hi:[0,1]
	v_pk_fma_f32 v[2:3], v[2:3], v[212:213], v[136:137] op_sel:[0,1,0] op_sel_hi:[1,1,1] neg_lo:[0,0,1]
	v_pk_mul_f32 v[8:9], v[8:9], s[36:37] op_sel_hi:[1,0]
	v_pk_mul_f32 v[10:11], v[10:11], s[36:37] op_sel_hi:[1,0]
	v_pk_mul_f32 v[0:1], v[0:1], s[36:37] op_sel_hi:[1,0]
	v_pk_mul_f32 v[2:3], v[2:3], s[36:37] op_sel_hi:[1,0]
	v_cvt_pk_bf16_f32 v144, v8, v9
	v_cvt_pk_bf16_f32 v145, v10, v11
	v_cvt_pk_bf16_f32 v146, v0, v1
	v_cvt_pk_bf16_f32 v147, v2, v3
	s_waitcnt lgkmcnt(0)
	global_store_dwordx4 v130, v[218:221], s[6:7] sc1
	global_store_dwordx4 v130, v[222:225], s[6:7] offset:64 sc1
	s_add_u32 s6, s6, s33
	s_addc_u32 s7, s7, 0
	ds_bpermute_b32 v226, v180, v140
	ds_bpermute_b32 v227, v180, v141
	ds_bpermute_b32 v228, v180, v142
	ds_bpermute_b32 v229, v180, v143
	ds_bpermute_b32 v230, v180, v144
	ds_bpermute_b32 v231, v180, v145
	ds_bpermute_b32 v232, v180, v146
	ds_bpermute_b32 v233, v180, v147
	s_waitcnt lgkmcnt(0)
	global_store_dwordx4 v130, v[226:229], s[6:7] sc1
	global_store_dwordx4 v130, v[230:233], s[6:7] offset:64 sc1
	s_branch .LBB0_638
.Lq3_B:
	global_load_dwordx4 v[148:151], v133, s[24:25]
	global_load_dwordx4 v[152:155], v133, s[24:25] offset:16
	global_load_dwordx4 v[156:159], v133, s[24:25] offset:128
	global_load_dwordx4 v[160:163], v133, s[24:25] offset:144
	v_mul_f32_e32 v134, v127, v127
	v_fmac_f32_e32 v134, v126, v126
	v_fmac_f32_e32 v134, v128, v128
	v_fmac_f32_e32 v134, v129, v129
	v_fmac_f32_e32 v134, v122, v122
	v_fmac_f32_e32 v134, v123, v123
	v_fmac_f32_e32 v134, v124, v124
	v_fmac_f32_e32 v134, v125, v125
	v_fmac_f32_e32 v134, v118, v118
	v_fmac_f32_e32 v134, v119, v119
	v_pk_mul_f32 v[136:137], v[120:121], v[120:121]
	v_pk_mul_f32 v[138:139], v[114:115], v[114:115]
	v_add_f32_e32 v134, v136, v134
	v_add_f32_e32 v134, v137, v134
	v_add_f32_e32 v134, v138, v134
	v_pk_mul_f32 v[136:137], v[116:117], v[116:117]
	v_add_f32_e32 v134, v139, v134
	v_add_f32_e32 v134, v136, v134
	v_add_f32_e32 v134, v137, v134
	ds_swizzle_b32 v135, v134 offset:swizzle(SWAP,16)
	s_waitcnt lgkmcnt(0)
	v_add_f32_e32 v134, v134, v135
	v_mov_b32_e32 v135, v134
	s_nop 1
	v_permlane32_swap_b32 v134, v135
	s_nop 1
	v_add_f32_e32 v134, v134, v135
	v_fmamk_f32 v134, v134, 0x3c800000, v242
	v_rsq_f32_e32 v134, v134
	s_waitcnt vmcnt(0)
	v_pk_mul_f32 v[136:137], v[134:135], v[148:149] op_sel_hi:[0,1]
	v_pk_mul_f32 v[126:127], v[126:127], v[136:137]
	v_pk_mul_f32 v[136:137], v[134:135], v[150:151] op_sel_hi:[0,1]
	v_pk_mul_f32 v[128:129], v[128:129], v[136:137]
	v_pk_mul_f32 v[136:137], v[134:135], v[152:153] op_sel_hi:[0,1]
	v_pk_mul_f32 v[122:123], v[122:123], v[136:137]
	v_pk_mul_f32 v[136:137], v[134:135], v[154:155] op_sel_hi:[0,1]
	v_pk_mul_f32 v[124:125], v[124:125], v[136:137]
	v_pk_mul_f32 v[136:137], v[134:135], v[156:157] op_sel_hi:[0,1]
	v_pk_mul_f32 v[118:119], v[118:119], v[136:137]
	v_pk_mul_f32 v[136:137], v[134:135], v[158:159] op_sel_hi:[0,1]
	v_pk_mul_f32 v[120:121], v[120:121], v[136:137]
	v_pk_mul_f32 v[136:137], v[134:135], v[160:161] op_sel_hi:[0,1]
	v_pk_mul_f32 v[114:115], v[114:115], v[136:137]
	v_pk_mul_f32 v[136:137], v[134:135], v[162:163] op_sel_hi:[0,1]
	v_pk_mul_f32 v[116:117], v[116:117], v[136:137]
	v_pk_mul_f32 v[126:127], v[126:127], s[36:37] op_sel_hi:[1,0]
	v_pk_mul_f32 v[128:129], v[128:129], s[36:37] op_sel_hi:[1,0]
	v_pk_mul_f32 v[122:123], v[122:123], s[36:37] op_sel_hi:[1,0]
	v_pk_mul_f32 v[124:125], v[124:125], s[36:37] op_sel_hi:[1,0]
	v_cvt_pk_bf16_f32 v140, v126, v127
	v_cvt_pk_bf16_f32 v141, v128, v129
	v_cvt_pk_bf16_f32 v142, v122, v123
	v_cvt_pk_bf16_f32 v143, v124, v125
	v_pk_mul_f32 v[118:119], v[118:119], s[36:37] op_sel_hi:[1,0]
	v_pk_mul_f32 v[120:121], v[120:121], s[36:37] op_sel_hi:[1,0]
	v_pk_mul_f32 v[114:115], v[114:115], s[36:37] op_sel_hi:[1,0]
	v_pk_mul_f32 v[116:117], v[116:117], s[36:37] op_sel_hi:[1,0]
	v_cvt_pk_bf16_f32 v144, v118, v119
	v_cvt_pk_bf16_f32 v145, v120, v121
	v_cvt_pk_bf16_f32 v146, v114, v115
	v_cvt_pk_bf16_f32 v147, v116, v117
	ds_bpermute_b32 v218, v180, v140
	ds_bpermute_b32 v219, v180, v141
	ds_bpermute_b32 v220, v180, v142
	ds_bpermute_b32 v221, v180, v143
	ds_bpermute_b32 v222, v180, v144
	ds_bpermute_b32 v223, v180, v145
	ds_bpermute_b32 v224, v180, v146
	ds_bpermute_b32 v225, v180, v147
	v_mul_f32_e32 v134, v109, v109
	v_fmac_f32_e32 v134, v108, v108
	v_fmac_f32_e32 v134, v110, v110
	v_fmac_f32_e32 v134, v111, v111
	v_fmac_f32_e32 v134, v104, v104
	v_fmac_f32_e32 v134, v105, v105
	v_fmac_f32_e32 v134, v106, v106
	v_fmac_f32_e32 v134, v107, v107
	v_fmac_f32_e32 v134, v100, v100
	v_fmac_f32_e32 v134, v101, v101
	v_pk_mul_f32 v[136:137], v[102:103], v[102:103]
	v_pk_mul_f32 v[138:139], v[96:97], v[96:97]
	v_add_f32_e32 v134, v136, v134
	v_add_f32_e32 v134, v137, v134
	v_add_f32_e32 v134, v138, v134
	v_pk_mul_f32 v[136:137], v[98:99], v[98:99]
	v_add_f32_e32 v134, v139, v134
	v_add_f32_e32 v134, v136, v134
	v_add_f32_e32 v134, v137, v134
	ds_swizzle_b32 v135, v134 offset:swizzle(SWAP,16)
	s_waitcnt lgkmcnt(0)
	v_add_f32_e32 v134, v134, v135
	v_mov_b32_e32 v135, v134
	s_nop 1
	v_permlane32_swap_b32 v134, v135
	s_nop 1
	v_add_f32_e32 v134, v134, v135
	v_fmamk_f32 v134, v134, 0x3c800000, v242
	v_rsq_f32_e32 v134, v134
	s_nop 0
	v_pk_mul_f32 v[136:137], v[134:135], v[148:149] op_sel_hi:[0,1]
	v_pk_mul_f32 v[108:109], v[108:109], v[136:137]
	v_pk_mul_f32 v[136:137], v[134:135], v[150:151] op_sel_hi:[0,1]
	v_pk_mul_f32 v[110:111], v[110:111], v[136:137]
	v_pk_mul_f32 v[136:137], v[134:135], v[152:153] op_sel_hi:[0,1]
	v_pk_mul_f32 v[104:105], v[104:105], v[136:137]
	v_pk_mul_f32 v[136:137], v[134:135], v[154:155] op_sel_hi:[0,1]
	v_pk_mul_f32 v[106:107], v[106:107], v[136:137]
	v_pk_mul_f32 v[136:137], v[134:135], v[156:157] op_sel_hi:[0,1]
	v_pk_mul_f32 v[100:101], v[100:101], v[136:137]
	v_pk_mul_f32 v[136:137], v[134:135], v[158:159] op_sel_hi:[0,1]
	v_pk_mul_f32 v[102:103], v[102:103], v[136:137]
	v_pk_mul_f32 v[136:137], v[134:135], v[160:161] op_sel_hi:[0,1]
	v_pk_mul_f32 v[96:97], v[96:97], v[136:137]
	v_pk_mul_f32 v[136:137], v[134:135], v[162:163] op_sel_hi:[0,1]
	v_pk_mul_f32 v[98:99], v[98:99], v[136:137]
	v_pk_mul_f32 v[108:109], v[108:109], s[36:37] op_sel_hi:[1,0]
	v_pk_mul_f32 v[110:111], v[110:111], s[36:37] op_sel_hi:[1,0]
	v_pk_mul_f32 v[104:105], v[104:105], s[36:37] op_sel_hi:[1,0]
	v_pk_mul_f32 v[106:107], v[106:107], s[36:37] op_sel_hi:[1,0]
	v_cvt_pk_bf16_f32 v140, v108, v109
	v_cvt_pk_bf16_f32 v141, v110, v111
	v_cvt_pk_bf16_f32 v142, v104, v105
	v_cvt_pk_bf16_f32 v143, v106, v107
	v_pk_mul_f32 v[100:101], v[100:101], s[36:37] op_sel_hi:[1,0]
	v_pk_mul_f32 v[102:103], v[102:103], s[36:37] op_sel_hi:[1,0]
	v_pk_mul_f32 v[96:97], v[96:97], s[36:37] op_sel_hi:[1,0]
	v_pk_mul_f32 v[98:99], v[98:99], s[36:37] op_sel_hi:[1,0]
	v_cvt_pk_bf16_f32 v144, v100, v101
	v_cvt_pk_bf16_f32 v145, v102, v103
	v_cvt_pk_bf16_f32 v146, v96, v97
	v_cvt_pk_bf16_f32 v147, v98, v99
	s_waitcnt lgkmcnt(0)
	global_store_dwordx4 v130, v[218:221], s[6:7] sc1
	global_store_dwordx4 v130, v[222:225], s[6:7] offset:64 sc1
	s_add_u32 s6, s6, s33
	s_addc_u32 s7, s7, 0
	ds_bpermute_b32 v226, v180, v140
	ds_bpermute_b32 v227, v180, v141
	ds_bpermute_b32 v228, v180, v142
	ds_bpermute_b32 v229, v180, v143
	ds_bpermute_b32 v230, v180, v144
	ds_bpermute_b32 v231, v180, v145
	ds_bpermute_b32 v232, v180, v146
	ds_bpermute_b32 v233, v180, v147
	v_mul_f32_e32 v134, v93, v93
	v_fmac_f32_e32 v134, v92, v92
	v_fmac_f32_e32 v134, v94, v94
	v_fmac_f32_e32 v134, v95, v95
	v_fmac_f32_e32 v134, v88, v88
	v_fmac_f32_e32 v134, v89, v89
	v_fmac_f32_e32 v134, v90, v90
	v_fmac_f32_e32 v134, v91, v91
	v_fmac_f32_e32 v134, v84, v84
	v_fmac_f32_e32 v134, v85, v85
	v_pk_mul_f32 v[136:137], v[86:87], v[86:87]
	v_pk_mul_f32 v[138:139], v[80:81], v[80:81]
	v_add_f32_e32 v134, v136, v134
	v_add_f32_e32 v134, v137, v134
	v_add_f32_e32 v134, v138, v134
	v_pk_mul_f32 v[136:137], v[82:83], v[82:83]
	v_add_f32_e32 v134, v139, v134
	v_add_f32_e32 v134, v136, v134
	v_add_f32_e32 v134, v137, v134
	ds_swizzle_b32 v135, v134 offset:swizzle(SWAP,16)
	s_waitcnt lgkmcnt(0)
	v_add_f32_e32 v134, v134, v135
	v_mov_b32_e32 v135, v134
	s_nop 1
	v_permlane32_swap_b32 v134, v135
	s_nop 1
	v_add_f32_e32 v134, v134, v135
	v_fmamk_f32 v134, v134, 0x3c800000, v242
	v_rsq_f32_e32 v134, v134
	s_nop 0
	v_pk_mul_f32 v[136:137], v[134:135], v[148:149] op_sel_hi:[0,1]
	v_pk_mul_f32 v[92:93], v[92:93], v[136:137]
	v_pk_mul_f32 v[136:137], v[134:135], v[150:151] op_sel_hi:[0,1]
	v_pk_mul_f32 v[94:95], v[94:95], v[136:137]
	v_pk_mul_f32 v[136:137], v[134:135], v[152:153] op_sel_hi:[0,1]
	v_pk_mul_f32 v[88:89], v[88:89], v[136:137]
	v_pk_mul_f32 v[136:137], v[134:135], v[154:155] op_sel_hi:[0,1]
	v_pk_mul_f32 v[90:91], v[90:91], v[136:137]
	v_pk_mul_f32 v[136:137], v[134:135], v[156:157] op_sel_hi:[0,1]
	v_pk_mul_f32 v[84:85], v[84:85], v[136:137]
	v_pk_mul_f32 v[136:137], v[134:135], v[158:159] op_sel_hi:[0,1]
	v_pk_mul_f32 v[86:87], v[86:87], v[136:137]
	v_pk_mul_f32 v[136:137], v[134:135], v[160:161] op_sel_hi:[0,1]
	v_pk_mul_f32 v[80:81], v[80:81], v[136:137]
	v_pk_mul_f32 v[136:137], v[134:135], v[162:163] op_sel_hi:[0,1]
	v_pk_mul_f32 v[82:83], v[82:83], v[136:137]
	v_pk_mul_f32 v[92:93], v[92:93], s[36:37] op_sel_hi:[1,0]
	v_pk_mul_f32 v[94:95], v[94:95], s[36:37] op_sel_hi:[1,0]
	v_pk_mul_f32 v[88:89], v[88:89], s[36:37] op_sel_hi:[1,0]
	v_pk_mul_f32 v[90:91], v[90:91], s[36:37] op_sel_hi:[1,0]
	v_cvt_pk_bf16_f32 v140, v92, v93
	v_cvt_pk_bf16_f32 v141, v94, v95
	v_cvt_pk_bf16_f32 v142, v88, v89
	v_cvt_pk_bf16_f32 v143, v90, v91
	v_pk_mul_f32 v[84:85], v[84:85], s[36:37] op_sel_hi:[1,0]
	v_pk_mul_f32 v[86:87], v[86:87], s[36:37] op_sel_hi:[1,0]
	v_pk_mul_f32 v[80:81], v[80:81], s[36:37] op_sel_hi:[1,0]
	v_pk_mul_f32 v[82:83], v[82:83], s[36:37] op_sel_hi:[1,0]
	v_cvt_pk_bf16_f32 v144, v84, v85
	v_cvt_pk_bf16_f32 v145, v86, v87
	v_cvt_pk_bf16_f32 v146, v80, v81
	v_cvt_pk_bf16_f32 v147, v82, v83
	s_waitcnt lgkmcnt(0)
	global_store_dwordx4 v130, v[226:229], s[6:7] sc1
	global_store_dwordx4 v130, v[230:233], s[6:7] offset:64 sc1
	s_add_u32 s6, s6, s33
	s_addc_u32 s7, s7, 0
	ds_bpermute_b32 v218, v180, v140
	ds_bpermute_b32 v219, v180, v141
	ds_bpermute_b32 v220, v180, v142
	ds_bpermute_b32 v221, v180, v143
	ds_bpermute_b32 v222, v180, v144
	ds_bpermute_b32 v223, v180, v145
	ds_bpermute_b32 v224, v180, v146
	ds_bpermute_b32 v225, v180, v147
	v_mul_f32_e32 v134, v77, v77
	v_fmac_f32_e32 v134, v76, v76
	v_fmac_f32_e32 v134, v78, v78
	v_fmac_f32_e32 v134, v79, v79
	v_fmac_f32_e32 v134, v72, v72
	v_fmac_f32_e32 v134, v73, v73
	v_fmac_f32_e32 v134, v74, v74
	v_fmac_f32_e32 v134, v75, v75
	v_fmac_f32_e32 v134, v68, v68
	v_fmac_f32_e32 v134, v69, v69
	v_pk_mul_f32 v[136:137], v[70:71], v[70:71]
	v_pk_mul_f32 v[138:139], v[64:65], v[64:65]
	v_add_f32_e32 v134, v136, v134
	v_add_f32_e32 v134, v137, v134
	v_add_f32_e32 v134, v138, v134
	v_pk_mul_f32 v[136:137], v[66:67], v[66:67]
	v_add_f32_e32 v134, v139, v134
	v_add_f32_e32 v134, v136, v134
	v_add_f32_e32 v134, v137, v134
	ds_swizzle_b32 v135, v134 offset:swizzle(SWAP,16)
	s_waitcnt lgkmcnt(0)
	v_add_f32_e32 v134, v134, v135
	v_mov_b32_e32 v135, v134
	s_nop 1
	v_permlane32_swap_b32 v134, v135
	s_nop 1
	v_add_f32_e32 v134, v134, v135
	v_fmamk_f32 v134, v134, 0x3c800000, v242
	v_rsq_f32_e32 v134, v134
	s_nop 0
	v_pk_mul_f32 v[136:137], v[134:135], v[148:149] op_sel_hi:[0,1]
	v_pk_mul_f32 v[76:77], v[76:77], v[136:137]
	v_pk_mul_f32 v[136:137], v[134:135], v[150:151] op_sel_hi:[0,1]
	v_pk_mul_f32 v[78:79], v[78:79], v[136:137]
	v_pk_mul_f32 v[136:137], v[134:135], v[152:153] op_sel_hi:[0,1]
	v_pk_mul_f32 v[72:73], v[72:73], v[136:137]
	v_pk_mul_f32 v[136:137], v[134:135], v[154:155] op_sel_hi:[0,1]
	v_pk_mul_f32 v[74:75], v[74:75], v[136:137]
	v_pk_mul_f32 v[136:137], v[134:135], v[156:157] op_sel_hi:[0,1]
	v_pk_mul_f32 v[68:69], v[68:69], v[136:137]
	v_pk_mul_f32 v[136:137], v[134:135], v[158:159] op_sel_hi:[0,1]
	v_pk_mul_f32 v[70:71], v[70:71], v[136:137]
	v_pk_mul_f32 v[136:137], v[134:135], v[160:161] op_sel_hi:[0,1]
	v_pk_mul_f32 v[64:65], v[64:65], v[136:137]
	v_pk_mul_f32 v[136:137], v[134:135], v[162:163] op_sel_hi:[0,1]
	v_pk_mul_f32 v[66:67], v[66:67], v[136:137]
	v_pk_mul_f32 v[76:77], v[76:77], s[36:37] op_sel_hi:[1,0]
	v_pk_mul_f32 v[78:79], v[78:79], s[36:37] op_sel_hi:[1,0]
	v_pk_mul_f32 v[72:73], v[72:73], s[36:37] op_sel_hi:[1,0]
	v_pk_mul_f32 v[74:75], v[74:75], s[36:37] op_sel_hi:[1,0]
	v_cvt_pk_bf16_f32 v140, v76, v77
	v_cvt_pk_bf16_f32 v141, v78, v79
	v_cvt_pk_bf16_f32 v142, v72, v73
	v_cvt_pk_bf16_f32 v143, v74, v75
	v_pk_mul_f32 v[68:69], v[68:69], s[36:37] op_sel_hi:[1,0]
	v_pk_mul_f32 v[70:71], v[70:71], s[36:37] op_sel_hi:[1,0]
	v_pk_mul_f32 v[64:65], v[64:65], s[36:37] op_sel_hi:[1,0]
	v_pk_mul_f32 v[66:67], v[66:67], s[36:37] op_sel_hi:[1,0]
	v_cvt_pk_bf16_f32 v144, v68, v69
	v_cvt_pk_bf16_f32 v145, v70, v71
	v_cvt_pk_bf16_f32 v146, v64, v65
	v_cvt_pk_bf16_f32 v147, v66, v67
	s_waitcnt lgkmcnt(0)
	global_store_dwordx4 v130, v[218:221], s[6:7] sc1
	global_store_dwordx4 v130, v[222:225], s[6:7] offset:64 sc1
	s_add_u32 s6, s6, s33
	s_addc_u32 s7, s7, 0
	ds_bpermute_b32 v226, v180, v140
	ds_bpermute_b32 v227, v180, v141
	ds_bpermute_b32 v228, v180, v142
	ds_bpermute_b32 v229, v180, v143
	ds_bpermute_b32 v230, v180, v144
	ds_bpermute_b32 v231, v180, v145
	ds_bpermute_b32 v232, v180, v146
	ds_bpermute_b32 v233, v180, v147
	v_mul_f32_e32 v134, v61, v61
	v_fmac_f32_e32 v134, v60, v60
	v_fmac_f32_e32 v134, v62, v62
	v_fmac_f32_e32 v134, v63, v63
	v_fmac_f32_e32 v134, v56, v56
	v_fmac_f32_e32 v134, v57, v57
	v_fmac_f32_e32 v134, v58, v58
	v_fmac_f32_e32 v134, v59, v59
	v_fmac_f32_e32 v134, v52, v52
	v_fmac_f32_e32 v134, v53, v53
	v_pk_mul_f32 v[136:137], v[54:55], v[54:55]
	v_pk_mul_f32 v[138:139], v[48:49], v[48:49]
	v_add_f32_e32 v134, v136, v134
	v_add_f32_e32 v134, v137, v134
	v_add_f32_e32 v134, v138, v134
	v_pk_mul_f32 v[136:137], v[50:51], v[50:51]
	v_add_f32_e32 v134, v139, v134
	v_add_f32_e32 v134, v136, v134
	v_add_f32_e32 v134, v137, v134
	ds_swizzle_b32 v135, v134 offset:swizzle(SWAP,16)
	s_waitcnt lgkmcnt(0)
	v_add_f32_e32 v134, v134, v135
	v_mov_b32_e32 v135, v134
	s_nop 1
	v_permlane32_swap_b32 v134, v135
	s_nop 1
	v_add_f32_e32 v134, v134, v135
	v_fmamk_f32 v134, v134, 0x3c800000, v242
	v_rsq_f32_e32 v134, v134
	s_nop 0
	v_pk_mul_f32 v[136:137], v[134:135], v[148:149] op_sel_hi:[0,1]
	v_pk_mul_f32 v[60:61], v[60:61], v[136:137]
	v_pk_mul_f32 v[136:137], v[134:135], v[150:151] op_sel_hi:[0,1]
	v_pk_mul_f32 v[62:63], v[62:63], v[136:137]
	v_pk_mul_f32 v[136:137], v[134:135], v[152:153] op_sel_hi:[0,1]
	v_pk_mul_f32 v[56:57], v[56:57], v[136:137]
	v_pk_mul_f32 v[136:137], v[134:135], v[154:155] op_sel_hi:[0,1]
	v_pk_mul_f32 v[58:59], v[58:59], v[136:137]
	v_pk_mul_f32 v[136:137], v[134:135], v[156:157] op_sel_hi:[0,1]
	v_pk_mul_f32 v[52:53], v[52:53], v[136:137]
	v_pk_mul_f32 v[136:137], v[134:135], v[158:159] op_sel_hi:[0,1]
	v_pk_mul_f32 v[54:55], v[54:55], v[136:137]
	v_pk_mul_f32 v[136:137], v[134:135], v[160:161] op_sel_hi:[0,1]
	v_pk_mul_f32 v[48:49], v[48:49], v[136:137]
	v_pk_mul_f32 v[136:137], v[134:135], v[162:163] op_sel_hi:[0,1]
	v_pk_mul_f32 v[50:51], v[50:51], v[136:137]
	v_pk_mul_f32 v[60:61], v[60:61], s[36:37] op_sel_hi:[1,0]
	v_pk_mul_f32 v[62:63], v[62:63], s[36:37] op_sel_hi:[1,0]
	v_pk_mul_f32 v[56:57], v[56:57], s[36:37] op_sel_hi:[1,0]
	v_pk_mul_f32 v[58:59], v[58:59], s[36:37] op_sel_hi:[1,0]
	v_cvt_pk_bf16_f32 v140, v60, v61
	v_cvt_pk_bf16_f32 v141, v62, v63
	v_cvt_pk_bf16_f32 v142, v56, v57
	v_cvt_pk_bf16_f32 v143, v58, v59
	v_pk_mul_f32 v[52:53], v[52:53], s[36:37] op_sel_hi:[1,0]
	v_pk_mul_f32 v[54:55], v[54:55], s[36:37] op_sel_hi:[1,0]
	v_pk_mul_f32 v[48:49], v[48:49], s[36:37] op_sel_hi:[1,0]
	v_pk_mul_f32 v[50:51], v[50:51], s[36:37] op_sel_hi:[1,0]
	v_cvt_pk_bf16_f32 v144, v52, v53
	v_cvt_pk_bf16_f32 v145, v54, v55
	v_cvt_pk_bf16_f32 v146, v48, v49
	v_cvt_pk_bf16_f32 v147, v50, v51
	s_waitcnt lgkmcnt(0)
	global_store_dwordx4 v130, v[226:229], s[6:7] sc1
	global_store_dwordx4 v130, v[230:233], s[6:7] offset:64 sc1
	s_add_u32 s6, s6, s34
	s_addc_u32 s7, s7, 0
	ds_bpermute_b32 v218, v180, v140
	ds_bpermute_b32 v219, v180, v141
	ds_bpermute_b32 v220, v180, v142
	ds_bpermute_b32 v221, v180, v143
	ds_bpermute_b32 v222, v180, v144
	ds_bpermute_b32 v223, v180, v145
	ds_bpermute_b32 v224, v180, v146
	ds_bpermute_b32 v225, v180, v147
	v_mul_f32_e32 v134, v45, v45
	v_fmac_f32_e32 v134, v44, v44
	v_fmac_f32_e32 v134, v46, v46
	v_fmac_f32_e32 v134, v47, v47
	v_fmac_f32_e32 v134, v40, v40
	v_fmac_f32_e32 v134, v41, v41
	v_fmac_f32_e32 v134, v42, v42
	v_fmac_f32_e32 v134, v43, v43
	v_fmac_f32_e32 v134, v36, v36
	v_fmac_f32_e32 v134, v37, v37
	v_pk_mul_f32 v[136:137], v[38:39], v[38:39]
	v_pk_mul_f32 v[138:139], v[32:33], v[32:33]
	v_add_f32_e32 v134, v136, v134
	v_add_f32_e32 v134, v137, v134
	v_add_f32_e32 v134, v138, v134
	v_pk_mul_f32 v[136:137], v[34:35], v[34:35]
	v_add_f32_e32 v134, v139, v134
	v_add_f32_e32 v134, v136, v134
	v_add_f32_e32 v134, v137, v134
	ds_swizzle_b32 v135, v134 offset:swizzle(SWAP,16)
	s_waitcnt lgkmcnt(0)
	v_add_f32_e32 v134, v134, v135
	v_mov_b32_e32 v135, v134
	s_nop 1
	v_permlane32_swap_b32 v134, v135
	s_nop 1
	v_add_f32_e32 v134, v134, v135
	v_fmamk_f32 v134, v134, 0x3c800000, v242
	v_rsq_f32_e32 v134, v134
	s_nop 0
	v_pk_mul_f32 v[136:137], v[134:135], v[148:149] op_sel_hi:[0,1]
	v_pk_mul_f32 v[44:45], v[44:45], v[136:137]
	v_pk_mul_f32 v[136:137], v[134:135], v[150:151] op_sel_hi:[0,1]
	v_pk_mul_f32 v[46:47], v[46:47], v[136:137]
	v_pk_mul_f32 v[136:137], v[134:135], v[152:153] op_sel_hi:[0,1]
	v_pk_mul_f32 v[40:41], v[40:41], v[136:137]
	v_pk_mul_f32 v[136:137], v[134:135], v[154:155] op_sel_hi:[0,1]
	v_pk_mul_f32 v[42:43], v[42:43], v[136:137]
	v_pk_mul_f32 v[136:137], v[134:135], v[156:157] op_sel_hi:[0,1]
	v_pk_mul_f32 v[36:37], v[36:37], v[136:137]
	v_pk_mul_f32 v[136:137], v[134:135], v[158:159] op_sel_hi:[0,1]
	v_pk_mul_f32 v[38:39], v[38:39], v[136:137]
	v_pk_mul_f32 v[136:137], v[134:135], v[160:161] op_sel_hi:[0,1]
	v_pk_mul_f32 v[32:33], v[32:33], v[136:137]
	v_pk_mul_f32 v[136:137], v[134:135], v[162:163] op_sel_hi:[0,1]
	v_pk_mul_f32 v[34:35], v[34:35], v[136:137]
	v_pk_mul_f32 v[44:45], v[44:45], s[36:37] op_sel_hi:[1,0]
	v_pk_mul_f32 v[46:47], v[46:47], s[36:37] op_sel_hi:[1,0]
	v_pk_mul_f32 v[40:41], v[40:41], s[36:37] op_sel_hi:[1,0]
	v_pk_mul_f32 v[42:43], v[42:43], s[36:37] op_sel_hi:[1,0]
	v_cvt_pk_bf16_f32 v140, v44, v45
	v_cvt_pk_bf16_f32 v141, v46, v47
	v_cvt_pk_bf16_f32 v142, v40, v41
	v_cvt_pk_bf16_f32 v143, v42, v43
	v_pk_mul_f32 v[36:37], v[36:37], s[36:37] op_sel_hi:[1,0]
	v_pk_mul_f32 v[38:39], v[38:39], s[36:37] op_sel_hi:[1,0]
	v_pk_mul_f32 v[32:33], v[32:33], s[36:37] op_sel_hi:[1,0]
	v_pk_mul_f32 v[34:35], v[34:35], s[36:37] op_sel_hi:[1,0]
	v_cvt_pk_bf16_f32 v144, v36, v37
	v_cvt_pk_bf16_f32 v145, v38, v39
	v_cvt_pk_bf16_f32 v146, v32, v33
	v_cvt_pk_bf16_f32 v147, v34, v35
	s_waitcnt lgkmcnt(0)
	global_store_dwordx4 v130, v[218:221], s[6:7] sc1
	global_store_dwordx4 v130, v[222:225], s[6:7] offset:64 sc1
	s_add_u32 s6, s6, s33
	s_addc_u32 s7, s7, 0
	ds_bpermute_b32 v226, v180, v140
	ds_bpermute_b32 v227, v180, v141
	ds_bpermute_b32 v228, v180, v142
	ds_bpermute_b32 v229, v180, v143
	ds_bpermute_b32 v230, v180, v144
	ds_bpermute_b32 v231, v180, v145
	ds_bpermute_b32 v232, v180, v146
	ds_bpermute_b32 v233, v180, v147
	v_mul_f32_e32 v134, v29, v29
	v_fmac_f32_e32 v134, v28, v28
	v_fmac_f32_e32 v134, v30, v30
	v_fmac_f32_e32 v134, v31, v31
	v_fmac_f32_e32 v134, v24, v24
	v_fmac_f32_e32 v134, v25, v25
	v_fmac_f32_e32 v134, v26, v26
	v_fmac_f32_e32 v134, v27, v27
	v_fmac_f32_e32 v134, v20, v20
	v_fmac_f32_e32 v134, v21, v21
	v_pk_mul_f32 v[136:137], v[22:23], v[22:23]
	v_pk_mul_f32 v[138:139], v[16:17], v[16:17]
	v_add_f32_e32 v134, v136, v134
	v_add_f32_e32 v134, v137, v134
	v_add_f32_e32 v134, v138, v134
	v_pk_mul_f32 v[136:137], v[18:19], v[18:19]
	v_add_f32_e32 v134, v139, v134
	v_add_f32_e32 v134, v136, v134
	v_add_f32_e32 v134, v137, v134
	ds_swizzle_b32 v135, v134 offset:swizzle(SWAP,16)
	s_waitcnt lgkmcnt(0)
	v_add_f32_e32 v134, v134, v135
	v_mov_b32_e32 v135, v134
	s_nop 1
	v_permlane32_swap_b32 v134, v135
	s_nop 1
	v_add_f32_e32 v134, v134, v135
	v_fmamk_f32 v134, v134, 0x3c800000, v242
	v_rsq_f32_e32 v134, v134
	s_nop 0
	v_pk_mul_f32 v[136:137], v[134:135], v[148:149] op_sel_hi:[0,1]
	v_pk_mul_f32 v[28:29], v[28:29], v[136:137]
	v_pk_mul_f32 v[136:137], v[134:135], v[150:151] op_sel_hi:[0,1]
	v_pk_mul_f32 v[30:31], v[30:31], v[136:137]
	v_pk_mul_f32 v[136:137], v[134:135], v[152:153] op_sel_hi:[0,1]
	v_pk_mul_f32 v[24:25], v[24:25], v[136:137]
	v_pk_mul_f32 v[136:137], v[134:135], v[154:155] op_sel_hi:[0,1]
	v_pk_mul_f32 v[26:27], v[26:27], v[136:137]
	v_pk_mul_f32 v[136:137], v[134:135], v[156:157] op_sel_hi:[0,1]
	v_pk_mul_f32 v[20:21], v[20:21], v[136:137]
	v_pk_mul_f32 v[136:137], v[134:135], v[158:159] op_sel_hi:[0,1]
	v_pk_mul_f32 v[22:23], v[22:23], v[136:137]
	v_pk_mul_f32 v[136:137], v[134:135], v[160:161] op_sel_hi:[0,1]
	v_pk_mul_f32 v[16:17], v[16:17], v[136:137]
	v_pk_mul_f32 v[136:137], v[134:135], v[162:163] op_sel_hi:[0,1]
	v_pk_mul_f32 v[18:19], v[18:19], v[136:137]
	v_pk_mul_f32 v[28:29], v[28:29], s[36:37] op_sel_hi:[1,0]
	v_pk_mul_f32 v[30:31], v[30:31], s[36:37] op_sel_hi:[1,0]
	v_pk_mul_f32 v[24:25], v[24:25], s[36:37] op_sel_hi:[1,0]
	v_pk_mul_f32 v[26:27], v[26:27], s[36:37] op_sel_hi:[1,0]
	v_cvt_pk_bf16_f32 v140, v28, v29
	v_cvt_pk_bf16_f32 v141, v30, v31
	v_cvt_pk_bf16_f32 v142, v24, v25
	v_cvt_pk_bf16_f32 v143, v26, v27
	v_pk_mul_f32 v[20:21], v[20:21], s[36:37] op_sel_hi:[1,0]
	v_pk_mul_f32 v[22:23], v[22:23], s[36:37] op_sel_hi:[1,0]
	v_pk_mul_f32 v[16:17], v[16:17], s[36:37] op_sel_hi:[1,0]
	v_pk_mul_f32 v[18:19], v[18:19], s[36:37] op_sel_hi:[1,0]
	v_cvt_pk_bf16_f32 v144, v20, v21
	v_cvt_pk_bf16_f32 v145, v22, v23
	v_cvt_pk_bf16_f32 v146, v16, v17
	v_cvt_pk_bf16_f32 v147, v18, v19
	s_waitcnt lgkmcnt(0)
	global_store_dwordx4 v130, v[226:229], s[6:7] sc1
	global_store_dwordx4 v130, v[230:233], s[6:7] offset:64 sc1
	s_add_u32 s6, s6, s33
	s_addc_u32 s7, s7, 0
	ds_bpermute_b32 v218, v180, v140
	ds_bpermute_b32 v219, v180, v141
	ds_bpermute_b32 v220, v180, v142
	ds_bpermute_b32 v221, v180, v143
	ds_bpermute_b32 v222, v180, v144
	ds_bpermute_b32 v223, v180, v145
	ds_bpermute_b32 v224, v180, v146
	ds_bpermute_b32 v225, v180, v147
	v_mul_f32_e32 v134, v13, v13
	v_fmac_f32_e32 v134, v12, v12
	v_fmac_f32_e32 v134, v14, v14
	v_fmac_f32_e32 v134, v15, v15
	v_fmac_f32_e32 v134, v4, v4
	v_fmac_f32_e32 v134, v5, v5
	v_fmac_f32_e32 v134, v6, v6
	v_fmac_f32_e32 v134, v7, v7
	v_fmac_f32_e32 v134, v8, v8
	v_fmac_f32_e32 v134, v9, v9
	v_pk_mul_f32 v[136:137], v[10:11], v[10:11]
	v_pk_mul_f32 v[138:139], v[0:1], v[0:1]
	v_add_f32_e32 v134, v136, v134
	v_add_f32_e32 v134, v137, v134
	v_add_f32_e32 v134, v138, v134
	v_pk_mul_f32 v[136:137], v[2:3], v[2:3]
	v_add_f32_e32 v134, v139, v134
	v_add_f32_e32 v134, v136, v134
	v_add_f32_e32 v134, v137, v134
	ds_swizzle_b32 v135, v134 offset:swizzle(SWAP,16)
	s_waitcnt lgkmcnt(0)
	v_add_f32_e32 v134, v134, v135
	v_mov_b32_e32 v135, v134
	s_nop 1
	v_permlane32_swap_b32 v134, v135
	s_nop 1
	v_add_f32_e32 v134, v134, v135
	v_fmamk_f32 v134, v134, 0x3c800000, v242
	v_rsq_f32_e32 v134, v134
	s_nop 0
	v_pk_mul_f32 v[136:137], v[134:135], v[148:149] op_sel_hi:[0,1]
	v_pk_mul_f32 v[12:13], v[12:13], v[136:137]
	v_pk_mul_f32 v[136:137], v[134:135], v[150:151] op_sel_hi:[0,1]
	v_pk_mul_f32 v[14:15], v[14:15], v[136:137]
	v_pk_mul_f32 v[136:137], v[134:135], v[152:153] op_sel_hi:[0,1]
	v_pk_mul_f32 v[4:5], v[4:5], v[136:137]
	v_pk_mul_f32 v[136:137], v[134:135], v[154:155] op_sel_hi:[0,1]
	v_pk_mul_f32 v[6:7], v[6:7], v[136:137]
	v_pk_mul_f32 v[136:137], v[134:135], v[156:157] op_sel_hi:[0,1]
	v_pk_mul_f32 v[8:9], v[8:9], v[136:137]
	v_pk_mul_f32 v[136:137], v[134:135], v[158:159] op_sel_hi:[0,1]
	v_pk_mul_f32 v[10:11], v[10:11], v[136:137]
	v_pk_mul_f32 v[136:137], v[134:135], v[160:161] op_sel_hi:[0,1]
	v_pk_mul_f32 v[0:1], v[0:1], v[136:137]
	v_pk_mul_f32 v[136:137], v[134:135], v[162:163] op_sel_hi:[0,1]
	v_pk_mul_f32 v[2:3], v[2:3], v[136:137]
	v_pk_mul_f32 v[12:13], v[12:13], s[36:37] op_sel_hi:[1,0]
	v_pk_mul_f32 v[14:15], v[14:15], s[36:37] op_sel_hi:[1,0]
	v_pk_mul_f32 v[4:5], v[4:5], s[36:37] op_sel_hi:[1,0]
	v_pk_mul_f32 v[6:7], v[6:7], s[36:37] op_sel_hi:[1,0]
	v_cvt_pk_bf16_f32 v140, v12, v13
	v_cvt_pk_bf16_f32 v141, v14, v15
	v_cvt_pk_bf16_f32 v142, v4, v5
	v_cvt_pk_bf16_f32 v143, v6, v7
	v_pk_mul_f32 v[8:9], v[8:9], s[36:37] op_sel_hi:[1,0]
	v_pk_mul_f32 v[10:11], v[10:11], s[36:37] op_sel_hi:[1,0]
	v_pk_mul_f32 v[0:1], v[0:1], s[36:37] op_sel_hi:[1,0]
	v_pk_mul_f32 v[2:3], v[2:3], s[36:37] op_sel_hi:[1,0]
	v_cvt_pk_bf16_f32 v144, v8, v9
	v_cvt_pk_bf16_f32 v145, v10, v11
	v_cvt_pk_bf16_f32 v146, v0, v1
	v_cvt_pk_bf16_f32 v147, v2, v3
	s_waitcnt lgkmcnt(0)
	global_store_dwordx4 v130, v[218:221], s[6:7] sc1
	global_store_dwordx4 v130, v[222:225], s[6:7] offset:64 sc1
	s_add_u32 s6, s6, s33
	s_addc_u32 s7, s7, 0
	ds_bpermute_b32 v226, v180, v140
	ds_bpermute_b32 v227, v180, v141
	ds_bpermute_b32 v228, v180, v142
	ds_bpermute_b32 v229, v180, v143
	ds_bpermute_b32 v230, v180, v144
	ds_bpermute_b32 v231, v180, v145
	ds_bpermute_b32 v232, v180, v146
	ds_bpermute_b32 v233, v180, v147
	s_waitcnt lgkmcnt(0)
	global_store_dwordx4 v130, v[226:229], s[6:7] sc1
	global_store_dwordx4 v130, v[230:233], s[6:7] offset:64 sc1
	s_branch .LBB0_638
.Lq3_C:
	global_load_dwordx4 v[164:167], v131, s[8:9]
	global_load_dwordx4 v[168:171], v132, s[8:9]
	global_load_dwordx4 v[172:175], v131, s[8:9] offset:64
	global_load_dwordx4 v[176:179], v132, s[8:9] offset:64
	s_add_u32 s8, s8, 0x800
	s_addc_u32 s9, s9, 0
	global_load_dwordx4 v[202:205], v131, s[8:9]
	global_load_dwordx4 v[206:209], v132, s[8:9]
	global_load_dwordx4 v[210:213], v131, s[8:9] offset:64
	global_load_dwordx4 v[214:217], v132, s[8:9] offset:64
	s_waitcnt vmcnt(4)
	v_pk_mul_f32 v[136:137], v[126:127], v[168:169] op_sel:[1,0] op_sel_hi:[0,0]
	v_pk_fma_f32 v[126:127], v[126:127], v[164:165], v[136:137] op_sel:[0,0,0] op_sel_hi:[1,0,1] neg_lo:[0,0,1]
	v_pk_mul_f32 v[136:137], v[128:129], v[168:169] op_sel:[1,1] op_sel_hi:[0,1]
	v_pk_fma_f32 v[128:129], v[128:129], v[164:165], v[136:137] op_sel:[0,1,0] op_sel_hi:[1,1,1] neg_lo:[0,0,1]
	v_pk_mul_f32 v[136:137], v[122:123], v[170:171] op_sel:[1,0] op_sel_hi:[0,0]
	v_pk_fma_f32 v[122:123], v[122:123], v[166:167], v[136:137] op_sel:[0,0,0] op_sel_hi:[1,0,1] neg_lo:[0,0,1]
	v_pk_mul_f32 v[136:137], v[124:125], v[170:171] op_sel:[1,1] op_sel_hi:[0,1]
	v_pk_fma_f32 v[124:125], v[124:125], v[166:167], v[136:137] op_sel:[0,1,0] op_sel_hi:[1,1,1] neg_lo:[0,0,1]
	v_pk_mul_f32 v[126:127], v[126:127], s[36:37] op_sel_hi:[1,0]
	v_pk_mul_f32 v[128:129], v[128:129], s[36:37] op_sel_hi:[1,0]
	v_pk_mul_f32 v[122:123], v[122:123], s[36:37] op_sel_hi:[1,0]
	v_pk_mul_f32 v[124:125], v[124:125], s[36:37] op_sel_hi:[1,0]
	v_cvt_pk_bf16_f32 v140, v126, v127
	v_cvt_pk_bf16_f32 v141, v128, v129
	v_cvt_pk_bf16_f32 v142, v122, v123
	v_cvt_pk_bf16_f32 v143, v124, v125
	v_pk_mul_f32 v[136:137], v[118:119], v[176:177] op_sel:[1,0] op_sel_hi:[0,0]
	v_pk_fma_f32 v[118:119], v[118:119], v[172:173], v[136:137] op_sel:[0,0,0] op_sel_hi:[1,0,1] neg_lo:[0,0,1]
	v_pk_mul_f32 v[136:137], v[120:121], v[176:177] op_sel:[1,1] op_sel_hi:[0,1]
	v_pk_fma_f32 v[120:121], v[120:121], v[172:173], v[136:137] op_sel:[0,1,0] op_sel_hi:[1,1,1] neg_lo:[0,0,1]
	v_pk_mul_f32 v[136:137], v[114:115], v[178:179] op_sel:[1,0] op_sel_hi:[0,0]
	v_pk_fma_f32 v[114:115], v[114:115], v[174:175], v[136:137] op_sel:[0,0,0] op_sel_hi:[1,0,1] neg_lo:[0,0,1]
	v_pk_mul_f32 v[136:137], v[116:117], v[178:179] op_sel:[1,1] op_sel_hi:[0,1]
	v_pk_fma_f32 v[116:117], v[116:117], v[174:175], v[136:137] op_sel:[0,1,0] op_sel_hi:[1,1,1] neg_lo:[0,0,1]
	v_pk_mul_f32 v[118:119], v[118:119], s[36:37] op_sel_hi:[1,0]
	v_pk_mul_f32 v[120:121], v[120:121], s[36:37] op_sel_hi:[1,0]
	v_pk_mul_f32 v[114:115], v[114:115], s[36:37] op_sel_hi:[1,0]
	v_pk_mul_f32 v[116:117], v[116:117], s[36:37] op_sel_hi:[1,0]
	v_cvt_pk_bf16_f32 v144, v118, v119
	v_cvt_pk_bf16_f32 v145, v120, v121
	v_cvt_pk_bf16_f32 v146, v114, v115
	v_cvt_pk_bf16_f32 v147, v116, v117
	ds_bpermute_b32 v218, v180, v140
	ds_bpermute_b32 v219, v180, v141
	ds_bpermute_b32 v220, v180, v142
	ds_bpermute_b32 v221, v180, v143
	ds_bpermute_b32 v222, v180, v144
	ds_bpermute_b32 v223, v180, v145
	ds_bpermute_b32 v224, v180, v146
	ds_bpermute_b32 v225, v180, v147
	s_add_u32 s8, s8, 0x800
	s_addc_u32 s9, s9, 0
	global_load_dwordx4 v[164:167], v131, s[8:9]
	global_load_dwordx4 v[168:171], v132, s[8:9]
	global_load_dwordx4 v[172:175], v131, s[8:9] offset:64
	global_load_dwordx4 v[176:179], v132, s[8:9] offset:64
	s_waitcnt vmcnt(4)
	v_pk_mul_f32 v[136:137], v[108:109], v[206:207] op_sel:[1,0] op_sel_hi:[0,0]
	v_pk_fma_f32 v[108:109], v[108:109], v[202:203], v[136:137] op_sel:[0,0,0] op_sel_hi:[1,0,1] neg_lo:[0,0,1]
	v_pk_mul_f32 v[136:137], v[110:111], v[206:207] op_sel:[1,1] op_sel_hi:[0,1]
	v_pk_fma_f32 v[110:111], v[110:111], v[202:203], v[136:137] op_sel:[0,1,0] op_sel_hi:[1,1,1] neg_lo:[0,0,1]
	v_pk_mul_f32 v[136:137], v[104:105], v[208:209] op_sel:[1,0] op_sel_hi:[0,0]
	v_pk_fma_f32 v[104:105], v[104:105], v[204:205], v[136:137] op_sel:[0,0,0] op_sel_hi:[1,0,1] neg_lo:[0,0,1]
	v_pk_mul_f32 v[136:137], v[106:107], v[208:209] op_sel:[1,1] op_sel_hi:[0,1]
	v_pk_fma_f32 v[106:107], v[106:107], v[204:205], v[136:137] op_sel:[0,1,0] op_sel_hi:[1,1,1] neg_lo:[0,0,1]
	v_pk_mul_f32 v[108:109], v[108:109], s[36:37] op_sel_hi:[1,0]
	v_pk_mul_f32 v[110:111], v[110:111], s[36:37] op_sel_hi:[1,0]
	v_pk_mul_f32 v[104:105], v[104:105], s[36:37] op_sel_hi:[1,0]
	v_pk_mul_f32 v[106:107], v[106:107], s[36:37] op_sel_hi:[1,0]
	v_cvt_pk_bf16_f32 v140, v108, v109
	v_cvt_pk_bf16_f32 v141, v110, v111
	v_cvt_pk_bf16_f32 v142, v104, v105
	v_cvt_pk_bf16_f32 v143, v106, v107
	v_pk_mul_f32 v[136:137], v[100:101], v[214:215] op_sel:[1,0] op_sel_hi:[0,0]
	v_pk_fma_f32 v[100:101], v[100:101], v[210:211], v[136:137] op_sel:[0,0,0] op_sel_hi:[1,0,1] neg_lo:[0,0,1]
	v_pk_mul_f32 v[136:137], v[102:103], v[214:215] op_sel:[1,1] op_sel_hi:[0,1]
	v_pk_fma_f32 v[102:103], v[102:103], v[210:211], v[136:137] op_sel:[0,1,0] op_sel_hi:[1,1,1] neg_lo:[0,0,1]
	v_pk_mul_f32 v[136:137], v[96:97], v[216:217] op_sel:[1,0] op_sel_hi:[0,0]
	v_pk_fma_f32 v[96:97], v[96:97], v[212:213], v[136:137] op_sel:[0,0,0] op_sel_hi:[1,0,1] neg_lo:[0,0,1]
	v_pk_mul_f32 v[136:137], v[98:99], v[216:217] op_sel:[1,1] op_sel_hi:[0,1]
	v_pk_fma_f32 v[98:99], v[98:99], v[212:213], v[136:137] op_sel:[0,1,0] op_sel_hi:[1,1,1] neg_lo:[0,0,1]
	v_pk_mul_f32 v[100:101], v[100:101], s[36:37] op_sel_hi:[1,0]
	v_pk_mul_f32 v[102:103], v[102:103], s[36:37] op_sel_hi:[1,0]
	v_pk_mul_f32 v[96:97], v[96:97], s[36:37] op_sel_hi:[1,0]
	v_pk_mul_f32 v[98:99], v[98:99], s[36:37] op_sel_hi:[1,0]
	v_cvt_pk_bf16_f32 v144, v100, v101
	v_cvt_pk_bf16_f32 v145, v102, v103
	v_cvt_pk_bf16_f32 v146, v96, v97
	v_cvt_pk_bf16_f32 v147, v98, v99
	s_waitcnt lgkmcnt(0)
	global_store_dwordx4 v130, v[218:221], s[6:7] sc1
	global_store_dwordx4 v130, v[222:225], s[6:7] offset:64 sc1
	s_add_u32 s6, s6, s33
	s_addc_u32 s7, s7, 0
	ds_bpermute_b32 v226, v180, v140
	ds_bpermute_b32 v227, v180, v141
	ds_bpermute_b32 v228, v180, v142
	ds_bpermute_b32 v229, v180, v143
	ds_bpermute_b32 v230, v180, v144
	ds_bpermute_b32 v231, v180, v145
	ds_bpermute_b32 v232, v180, v146
	ds_bpermute_b32 v233, v180, v147
	s_add_u32 s8, s8, 0x800
	s_addc_u32 s9, s9, 0
	global_load_dwordx4 v[202:205], v131, s[8:9]
	global_load_dwordx4 v[206:209], v132, s[8:9]
	global_load_dwordx4 v[210:213], v131, s[8:9] offset:64
	global_load_dwordx4 v[214:217], v132, s[8:9] offset:64
	s_waitcnt vmcnt(6)
	v_pk_mul_f32 v[136:137], v[92:93], v[168:169] op_sel:[1,0] op_sel_hi:[0,0]
	v_pk_fma_f32 v[92:93], v[92:93], v[164:165], v[136:137] op_sel:[0,0,0] op_sel_hi:[1,0,1] neg_lo:[0,0,1]
	v_pk_mul_f32 v[136:137], v[94:95], v[168:169] op_sel:[1,1] op_sel_hi:[0,1]
	v_pk_fma_f32 v[94:95], v[94:95], v[164:165], v[136:137] op_sel:[0,1,0] op_sel_hi:[1,1,1] neg_lo:[0,0,1]
	v_pk_mul_f32 v[136:137], v[88:89], v[170:171] op_sel:[1,0] op_sel_hi:[0,0]
	v_pk_fma_f32 v[88:89], v[88:89], v[166:167], v[136:137] op_sel:[0,0,0] op_sel_hi:[1,0,1] neg_lo:[0,0,1]
	v_pk_mul_f32 v[136:137], v[90:91], v[170:171] op_sel:[1,1] op_sel_hi:[0,1]
	v_pk_fma_f32 v[90:91], v[90:91], v[166:167], v[136:137] op_sel:[0,1,0] op_sel_hi:[1,1,1] neg_lo:[0,0,1]
	v_pk_mul_f32 v[92:93], v[92:93], s[36:37] op_sel_hi:[1,0]
	v_pk_mul_f32 v[94:95], v[94:95], s[36:37] op_sel_hi:[1,0]
	v_pk_mul_f32 v[88:89], v[88:89], s[36:37] op_sel_hi:[1,0]
	v_pk_mul_f32 v[90:91], v[90:91], s[36:37] op_sel_hi:[1,0]
	v_cvt_pk_bf16_f32 v140, v92, v93
	v_cvt_pk_bf16_f32 v141, v94, v95
	v_cvt_pk_bf16_f32 v142, v88, v89
	v_cvt_pk_bf16_f32 v143, v90, v91
	v_pk_mul_f32 v[136:137], v[84:85], v[176:177] op_sel:[1,0] op_sel_hi:[0,0]
	v_pk_fma_f32 v[84:85], v[84:85], v[172:173], v[136:137] op_sel:[0,0,0] op_sel_hi:[1,0,1] neg_lo:[0,0,1]
	v_pk_mul_f32 v[136:137], v[86:87], v[176:177] op_sel:[1,1] op_sel_hi:[0,1]
	v_pk_fma_f32 v[86:87], v[86:87], v[172:173], v[136:137] op_sel:[0,1,0] op_sel_hi:[1,1,1] neg_lo:[0,0,1]
	v_pk_mul_f32 v[136:137], v[80:81], v[178:179] op_sel:[1,0] op_sel_hi:[0,0]
	v_pk_fma_f32 v[80:81], v[80:81], v[174:175], v[136:137] op_sel:[0,0,0] op_sel_hi:[1,0,1] neg_lo:[0,0,1]
	v_pk_mul_f32 v[136:137], v[82:83], v[178:179] op_sel:[1,1] op_sel_hi:[0,1]
	v_pk_fma_f32 v[82:83], v[82:83], v[174:175], v[136:137] op_sel:[0,1,0] op_sel_hi:[1,1,1] neg_lo:[0,0,1]
	v_pk_mul_f32 v[84:85], v[84:85], s[36:37] op_sel_hi:[1,0]
	v_pk_mul_f32 v[86:87], v[86:87], s[36:37] op_sel_hi:[1,0]
	v_pk_mul_f32 v[80:81], v[80:81], s[36:37] op_sel_hi:[1,0]
	v_pk_mul_f32 v[82:83], v[82:83], s[36:37] op_sel_hi:[1,0]
	v_cvt_pk_bf16_f32 v144, v84, v85
	v_cvt_pk_bf16_f32 v145, v86, v87
	v_cvt_pk_bf16_f32 v146, v80, v81
	v_cvt_pk_bf16_f32 v147, v82, v83
	s_waitcnt lgkmcnt(0)
	global_store_dwordx4 v130, v[226:229], s[6:7] sc1
	global_store_dwordx4 v130, v[230:233], s[6:7] offset:64 sc1
	s_add_u32 s6, s6, s33
	s_addc_u32 s7, s7, 0
	ds_bpermute_b32 v218, v180, v140
	ds_bpermute_b32 v219, v180, v141
	ds_bpermute_b32 v220, v180, v142
	ds_bpermute_b32 v221, v180, v143
	ds_bpermute_b32 v222, v180, v144
	ds_bpermute_b32 v223, v180, v145
	ds_bpermute_b32 v224, v180, v146
	ds_bpermute_b32 v225, v180, v147
	s_add_u32 s8, s8, 0x2800
	s_addc_u32 s9, s9, 0
	global_load_dwordx4 v[164:167], v131, s[8:9]
	global_load_dwordx4 v[168:171], v132, s[8:9]
	global_load_dwordx4 v[172:175], v131, s[8:9] offset:64
	global_load_dwordx4 v[176:179], v132, s[8:9] offset:64
	s_waitcnt vmcnt(6)
	v_pk_mul_f32 v[136:137], v[76:77], v[206:207] op_sel:[1,0] op_sel_hi:[0,0]
	v_pk_fma_f32 v[76:77], v[76:77], v[202:203], v[136:137] op_sel:[0,0,0] op_sel_hi:[1,0,1] neg_lo:[0,0,1]
	v_pk_mul_f32 v[136:137], v[78:79], v[206:207] op_sel:[1,1] op_sel_hi:[0,1]
	v_pk_fma_f32 v[78:79], v[78:79], v[202:203], v[136:137] op_sel:[0,1,0] op_sel_hi:[1,1,1] neg_lo:[0,0,1]
	v_pk_mul_f32 v[136:137], v[72:73], v[208:209] op_sel:[1,0] op_sel_hi:[0,0]
	v_pk_fma_f32 v[72:73], v[72:73], v[204:205], v[136:137] op_sel:[0,0,0] op_sel_hi:[1,0,1] neg_lo:[0,0,1]
	v_pk_mul_f32 v[136:137], v[74:75], v[208:209] op_sel:[1,1] op_sel_hi:[0,1]
	v_pk_fma_f32 v[74:75], v[74:75], v[204:205], v[136:137] op_sel:[0,1,0] op_sel_hi:[1,1,1] neg_lo:[0,0,1]
	v_pk_mul_f32 v[76:77], v[76:77], s[36:37] op_sel_hi:[1,0]
	v_pk_mul_f32 v[78:79], v[78:79], s[36:37] op_sel_hi:[1,0]
	v_pk_mul_f32 v[72:73], v[72:73], s[36:37] op_sel_hi:[1,0]
	v_pk_mul_f32 v[74:75], v[74:75], s[36:37] op_sel_hi:[1,0]
	v_cvt_pk_bf16_f32 v140, v76, v77
	v_cvt_pk_bf16_f32 v141, v78, v79
	v_cvt_pk_bf16_f32 v142, v72, v73
	v_cvt_pk_bf16_f32 v143, v74, v75
	v_pk_mul_f32 v[136:137], v[68:69], v[214:215] op_sel:[1,0] op_sel_hi:[0,0]
	v_pk_fma_f32 v[68:69], v[68:69], v[210:211], v[136:137] op_sel:[0,0,0] op_sel_hi:[1,0,1] neg_lo:[0,0,1]
	v_pk_mul_f32 v[136:137], v[70:71], v[214:215] op_sel:[1,1] op_sel_hi:[0,1]
	v_pk_fma_f32 v[70:71], v[70:71], v[210:211], v[136:137] op_sel:[0,1,0] op_sel_hi:[1,1,1] neg_lo:[0,0,1]
	v_pk_mul_f32 v[136:137], v[64:65], v[216:217] op_sel:[1,0] op_sel_hi:[0,0]
	v_pk_fma_f32 v[64:65], v[64:65], v[212:213], v[136:137] op_sel:[0,0,0] op_sel_hi:[1,0,1] neg_lo:[0,0,1]
	v_pk_mul_f32 v[136:137], v[66:67], v[216:217] op_sel:[1,1] op_sel_hi:[0,1]
	v_pk_fma_f32 v[66:67], v[66:67], v[212:213], v[136:137] op_sel:[0,1,0] op_sel_hi:[1,1,1] neg_lo:[0,0,1]
	v_pk_mul_f32 v[68:69], v[68:69], s[36:37] op_sel_hi:[1,0]
	v_pk_mul_f32 v[70:71], v[70:71], s[36:37] op_sel_hi:[1,0]
	v_pk_mul_f32 v[64:65], v[64:65], s[36:37] op_sel_hi:[1,0]
	v_pk_mul_f32 v[66:67], v[66:67], s[36:37] op_sel_hi:[1,0]
	v_cvt_pk_bf16_f32 v144, v68, v69
	v_cvt_pk_bf16_f32 v145, v70, v71
	v_cvt_pk_bf16_f32 v146, v64, v65
	v_cvt_pk_bf16_f32 v147, v66, v67
	s_waitcnt lgkmcnt(0)
	global_store_dwordx4 v130, v[218:221], s[6:7] sc1
	global_store_dwordx4 v130, v[222:225], s[6:7] offset:64 sc1
	s_add_u32 s6, s6, s33
	s_addc_u32 s7, s7, 0
	ds_bpermute_b32 v226, v180, v140
	ds_bpermute_b32 v227, v180, v141
	ds_bpermute_b32 v228, v180, v142
	ds_bpermute_b32 v229, v180, v143
	ds_bpermute_b32 v230, v180, v144
	ds_bpermute_b32 v231, v180, v145
	ds_bpermute_b32 v232, v180, v146
	ds_bpermute_b32 v233, v180, v147
	s_add_u32 s8, s8, 0x800
	s_addc_u32 s9, s9, 0
	global_load_dwordx4 v[202:205], v131, s[8:9]
	global_load_dwordx4 v[206:209], v132, s[8:9]
	global_load_dwordx4 v[210:213], v131, s[8:9] offset:64
	global_load_dwordx4 v[214:217], v132, s[8:9] offset:64
	s_waitcnt vmcnt(6)
	v_pk_mul_f32 v[136:137], v[60:61], v[168:169] op_sel:[1,0] op_sel_hi:[0,0]
	v_pk_fma_f32 v[60:61], v[60:61], v[164:165], v[136:137] op_sel:[0,0,0] op_sel_hi:[1,0,1] neg_lo:[0,0,1]
	v_pk_mul_f32 v[136:137], v[62:63], v[168:169] op_sel:[1,1] op_sel_hi:[0,1]
	v_pk_fma_f32 v[62:63], v[62:63], v[164:165], v[136:137] op_sel:[0,1,0] op_sel_hi:[1,1,1] neg_lo:[0,0,1]
	v_pk_mul_f32 v[136:137], v[56:57], v[170:171] op_sel:[1,0] op_sel_hi:[0,0]
	v_pk_fma_f32 v[56:57], v[56:57], v[166:167], v[136:137] op_sel:[0,0,0] op_sel_hi:[1,0,1] neg_lo:[0,0,1]
	v_pk_mul_f32 v[136:137], v[58:59], v[170:171] op_sel:[1,1] op_sel_hi:[0,1]
	v_pk_fma_f32 v[58:59], v[58:59], v[166:167], v[136:137] op_sel:[0,1,0] op_sel_hi:[1,1,1] neg_lo:[0,0,1]
	v_pk_mul_f32 v[60:61], v[60:61], s[36:37] op_sel_hi:[1,0]
	v_pk_mul_f32 v[62:63], v[62:63], s[36:37] op_sel_hi:[1,0]
	v_pk_mul_f32 v[56:57], v[56:57], s[36:37] op_sel_hi:[1,0]
	v_pk_mul_f32 v[58:59], v[58:59], s[36:37] op_sel_hi:[1,0]
	v_cvt_pk_bf16_f32 v140, v60, v61
	v_cvt_pk_bf16_f32 v141, v62, v63
	v_cvt_pk_bf16_f32 v142, v56, v57
	v_cvt_pk_bf16_f32 v143, v58, v59
	v_pk_mul_f32 v[136:137], v[52:53], v[176:177] op_sel:[1,0] op_sel_hi:[0,0]
	v_pk_fma_f32 v[52:53], v[52:53], v[172:173], v[136:137] op_sel:[0,0,0] op_sel_hi:[1,0,1] neg_lo:[0,0,1]
	v_pk_mul_f32 v[136:137], v[54:55], v[176:177] op_sel:[1,1] op_sel_hi:[0,1]
	v_pk_fma_f32 v[54:55], v[54:55], v[172:173], v[136:137] op_sel:[0,1,0] op_sel_hi:[1,1,1] neg_lo:[0,0,1]
	v_pk_mul_f32 v[136:137], v[48:49], v[178:179] op_sel:[1,0] op_sel_hi:[0,0]
	v_pk_fma_f32 v[48:49], v[48:49], v[174:175], v[136:137] op_sel:[0,0,0] op_sel_hi:[1,0,1] neg_lo:[0,0,1]
	v_pk_mul_f32 v[136:137], v[50:51], v[178:179] op_sel:[1,1] op_sel_hi:[0,1]
	v_pk_fma_f32 v[50:51], v[50:51], v[174:175], v[136:137] op_sel:[0,1,0] op_sel_hi:[1,1,1] neg_lo:[0,0,1]
	v_pk_mul_f32 v[52:53], v[52:53], s[36:37] op_sel_hi:[1,0]
	v_pk_mul_f32 v[54:55], v[54:55], s[36:37] op_sel_hi:[1,0]
	v_pk_mul_f32 v[48:49], v[48:49], s[36:37] op_sel_hi:[1,0]
	v_pk_mul_f32 v[50:51], v[50:51], s[36:37] op_sel_hi:[1,0]
	v_cvt_pk_bf16_f32 v144, v52, v53
	v_cvt_pk_bf16_f32 v145, v54, v55
	v_cvt_pk_bf16_f32 v146, v48, v49
	v_cvt_pk_bf16_f32 v147, v50, v51
	s_waitcnt lgkmcnt(0)
	global_store_dwordx4 v130, v[226:229], s[6:7] sc1
	global_store_dwordx4 v130, v[230:233], s[6:7] offset:64 sc1
	s_add_u32 s6, s6, s34
	s_addc_u32 s7, s7, 0
	ds_bpermute_b32 v218, v180, v140
	ds_bpermute_b32 v219, v180, v141
	ds_bpermute_b32 v220, v180, v142
	ds_bpermute_b32 v221, v180, v143
	ds_bpermute_b32 v222, v180, v144
	ds_bpermute_b32 v223, v180, v145
	ds_bpermute_b32 v224, v180, v146
	ds_bpermute_b32 v225, v180, v147
	s_add_u32 s8, s8, 0x800
	s_addc_u32 s9, s9, 0
	global_load_dwordx4 v[164:167], v131, s[8:9]
	global_load_dwordx4 v[168:171], v132, s[8:9]
	global_load_dwordx4 v[172:175], v131, s[8:9] offset:64
	global_load_dwordx4 v[176:179], v132, s[8:9] offset:64
	s_waitcnt vmcnt(6)
	v_pk_mul_f32 v[136:137], v[44:45], v[206:207] op_sel:[1,0] op_sel_hi:[0,0]
	v_pk_fma_f32 v[44:45], v[44:45], v[202:203], v[136:137] op_sel:[0,0,0] op_sel_hi:[1,0,1] neg_lo:[0,0,1]
	v_pk_mul_f32 v[136:137], v[46:47], v[206:207] op_sel:[1,1] op_sel_hi:[0,1]
	v_pk_fma_f32 v[46:47], v[46:47], v[202:203], v[136:137] op_sel:[0,1,0] op_sel_hi:[1,1,1] neg_lo:[0,0,1]
	v_pk_mul_f32 v[136:137], v[40:41], v[208:209] op_sel:[1,0] op_sel_hi:[0,0]
	v_pk_fma_f32 v[40:41], v[40:41], v[204:205], v[136:137] op_sel:[0,0,0] op_sel_hi:[1,0,1] neg_lo:[0,0,1]
	v_pk_mul_f32 v[136:137], v[42:43], v[208:209] op_sel:[1,1] op_sel_hi:[0,1]
	v_pk_fma_f32 v[42:43], v[42:43], v[204:205], v[136:137] op_sel:[0,1,0] op_sel_hi:[1,1,1] neg_lo:[0,0,1]
	v_pk_mul_f32 v[44:45], v[44:45], s[36:37] op_sel_hi:[1,0]
	v_pk_mul_f32 v[46:47], v[46:47], s[36:37] op_sel_hi:[1,0]
	v_pk_mul_f32 v[40:41], v[40:41], s[36:37] op_sel_hi:[1,0]
	v_pk_mul_f32 v[42:43], v[42:43], s[36:37] op_sel_hi:[1,0]
	v_cvt_pk_bf16_f32 v140, v44, v45
	v_cvt_pk_bf16_f32 v141, v46, v47
	v_cvt_pk_bf16_f32 v142, v40, v41
	v_cvt_pk_bf16_f32 v143, v42, v43
	v_pk_mul_f32 v[136:137], v[36:37], v[214:215] op_sel:[1,0] op_sel_hi:[0,0]
	v_pk_fma_f32 v[36:37], v[36:37], v[210:211], v[136:137] op_sel:[0,0,0] op_sel_hi:[1,0,1] neg_lo:[0,0,1]
	v_pk_mul_f32 v[136:137], v[38:39], v[214:215] op_sel:[1,1] op_sel_hi:[0,1]
	v_pk_fma_f32 v[38:39], v[38:39], v[210:211], v[136:137] op_sel:[0,1,0] op_sel_hi:[1,1,1] neg_lo:[0,0,1]
	v_pk_mul_f32 v[136:137], v[32:33], v[216:217] op_sel:[1,0] op_sel_hi:[0,0]
	v_pk_fma_f32 v[32:33], v[32:33], v[212:213], v[136:137] op_sel:[0,0,0] op_sel_hi:[1,0,1] neg_lo:[0,0,1]
	v_pk_mul_f32 v[136:137], v[34:35], v[216:217] op_sel:[1,1] op_sel_hi:[0,1]
	v_pk_fma_f32 v[34:35], v[34:35], v[212:213], v[136:137] op_sel:[0,1,0] op_sel_hi:[1,1,1] neg_lo:[0,0,1]
	v_pk_mul_f32 v[36:37], v[36:37], s[36:37] op_sel_hi:[1,0]
	v_pk_mul_f32 v[38:39], v[38:39], s[36:37] op_sel_hi:[1,0]
	v_pk_mul_f32 v[32:33], v[32:33], s[36:37] op_sel_hi:[1,0]
	v_pk_mul_f32 v[34:35], v[34:35], s[36:37] op_sel_hi:[1,0]
	v_cvt_pk_bf16_f32 v144, v36, v37
	v_cvt_pk_bf16_f32 v145, v38, v39
	v_cvt_pk_bf16_f32 v146, v32, v33
	v_cvt_pk_bf16_f32 v147, v34, v35
	s_waitcnt lgkmcnt(0)
	global_store_dwordx4 v130, v[218:221], s[6:7] sc1
	global_store_dwordx4 v130, v[222:225], s[6:7] offset:64 sc1
	s_add_u32 s6, s6, s33
	s_addc_u32 s7, s7, 0
	ds_bpermute_b32 v226, v180, v140
	ds_bpermute_b32 v227, v180, v141
	ds_bpermute_b32 v228, v180, v142
	ds_bpermute_b32 v229, v180, v143
	ds_bpermute_b32 v230, v180, v144
	ds_bpermute_b32 v231, v180, v145
	ds_bpermute_b32 v232, v180, v146
	ds_bpermute_b32 v233, v180, v147
	s_add_u32 s8, s8, 0x800
	s_addc_u32 s9, s9, 0
	global_load_dwordx4 v[202:205], v131, s[8:9]
	global_load_dwordx4 v[206:209], v132, s[8:9]
	global_load_dwordx4 v[210:213], v131, s[8:9] offset:64
	global_load_dwordx4 v[214:217], v132, s[8:9] offset:64
	s_waitcnt vmcnt(6)
	v_pk_mul_f32 v[136:137], v[28:29], v[168:169] op_sel:[1,0] op_sel_hi:[0,0]
	v_pk_fma_f32 v[28:29], v[28:29], v[164:165], v[136:137] op_sel:[0,0,0] op_sel_hi:[1,0,1] neg_lo:[0,0,1]
	v_pk_mul_f32 v[136:137], v[30:31], v[168:169] op_sel:[1,1] op_sel_hi:[0,1]
	v_pk_fma_f32 v[30:31], v[30:31], v[164:165], v[136:137] op_sel:[0,1,0] op_sel_hi:[1,1,1] neg_lo:[0,0,1]
	v_pk_mul_f32 v[136:137], v[24:25], v[170:171] op_sel:[1,0] op_sel_hi:[0,0]
	v_pk_fma_f32 v[24:25], v[24:25], v[166:167], v[136:137] op_sel:[0,0,0] op_sel_hi:[1,0,1] neg_lo:[0,0,1]
	v_pk_mul_f32 v[136:137], v[26:27], v[170:171] op_sel:[1,1] op_sel_hi:[0,1]
	v_pk_fma_f32 v[26:27], v[26:27], v[166:167], v[136:137] op_sel:[0,1,0] op_sel_hi:[1,1,1] neg_lo:[0,0,1]
	v_pk_mul_f32 v[28:29], v[28:29], s[36:37] op_sel_hi:[1,0]
	v_pk_mul_f32 v[30:31], v[30:31], s[36:37] op_sel_hi:[1,0]
	v_pk_mul_f32 v[24:25], v[24:25], s[36:37] op_sel_hi:[1,0]
	v_pk_mul_f32 v[26:27], v[26:27], s[36:37] op_sel_hi:[1,0]
	v_cvt_pk_bf16_f32 v140, v28, v29
	v_cvt_pk_bf16_f32 v141, v30, v31
	v_cvt_pk_bf16_f32 v142, v24, v25
	v_cvt_pk_bf16_f32 v143, v26, v27
	v_pk_mul_f32 v[136:137], v[20:21], v[176:177] op_sel:[1,0] op_sel_hi:[0,0]
	v_pk_fma_f32 v[20:21], v[20:21], v[172:173], v[136:137] op_sel:[0,0,0] op_sel_hi:[1,0,1] neg_lo:[0,0,1]
	v_pk_mul_f32 v[136:137], v[22:23], v[176:177] op_sel:[1,1] op_sel_hi:[0,1]
	v_pk_fma_f32 v[22:23], v[22:23], v[172:173], v[136:137] op_sel:[0,1,0] op_sel_hi:[1,1,1] neg_lo:[0,0,1]
	v_pk_mul_f32 v[136:137], v[16:17], v[178:179] op_sel:[1,0] op_sel_hi:[0,0]
	v_pk_fma_f32 v[16:17], v[16:17], v[174:175], v[136:137] op_sel:[0,0,0] op_sel_hi:[1,0,1] neg_lo:[0,0,1]
	v_pk_mul_f32 v[136:137], v[18:19], v[178:179] op_sel:[1,1] op_sel_hi:[0,1]
	v_pk_fma_f32 v[18:19], v[18:19], v[174:175], v[136:137] op_sel:[0,1,0] op_sel_hi:[1,1,1] neg_lo:[0,0,1]
	v_pk_mul_f32 v[20:21], v[20:21], s[36:37] op_sel_hi:[1,0]
	v_pk_mul_f32 v[22:23], v[22:23], s[36:37] op_sel_hi:[1,0]
	v_pk_mul_f32 v[16:17], v[16:17], s[36:37] op_sel_hi:[1,0]
	v_pk_mul_f32 v[18:19], v[18:19], s[36:37] op_sel_hi:[1,0]
	v_cvt_pk_bf16_f32 v144, v20, v21
	v_cvt_pk_bf16_f32 v145, v22, v23
	v_cvt_pk_bf16_f32 v146, v16, v17
	v_cvt_pk_bf16_f32 v147, v18, v19
	s_waitcnt lgkmcnt(0)
	global_store_dwordx4 v130, v[226:229], s[6:7] sc1
	global_store_dwordx4 v130, v[230:233], s[6:7] offset:64 sc1
	s_add_u32 s6, s6, s33
	s_addc_u32 s7, s7, 0
	ds_bpermute_b32 v218, v180, v140
	ds_bpermute_b32 v219, v180, v141
	ds_bpermute_b32 v220, v180, v142
	ds_bpermute_b32 v221, v180, v143
	ds_bpermute_b32 v222, v180, v144
	ds_bpermute_b32 v223, v180, v145
	ds_bpermute_b32 v224, v180, v146
	ds_bpermute_b32 v225, v180, v147
	s_waitcnt vmcnt(2)
	v_pk_mul_f32 v[136:137], v[12:13], v[206:207] op_sel:[1,0] op_sel_hi:[0,0]
	v_pk_fma_f32 v[12:13], v[12:13], v[202:203], v[136:137] op_sel:[0,0,0] op_sel_hi:[1,0,1] neg_lo:[0,0,1]
	v_pk_mul_f32 v[136:137], v[14:15], v[206:207] op_sel:[1,1] op_sel_hi:[0,1]
	v_pk_fma_f32 v[14:15], v[14:15], v[202:203], v[136:137] op_sel:[0,1,0] op_sel_hi:[1,1,1] neg_lo:[0,0,1]
	v_pk_mul_f32 v[136:137], v[4:5], v[208:209] op_sel:[1,0] op_sel_hi:[0,0]
	v_pk_fma_f32 v[4:5], v[4:5], v[204:205], v[136:137] op_sel:[0,0,0] op_sel_hi:[1,0,1] neg_lo:[0,0,1]
	v_pk_mul_f32 v[136:137], v[6:7], v[208:209] op_sel:[1,1] op_sel_hi:[0,1]
	v_pk_fma_f32 v[6:7], v[6:7], v[204:205], v[136:137] op_sel:[0,1,0] op_sel_hi:[1,1,1] neg_lo:[0,0,1]
	v_pk_mul_f32 v[12:13], v[12:13], s[36:37] op_sel_hi:[1,0]
	v_pk_mul_f32 v[14:15], v[14:15], s[36:37] op_sel_hi:[1,0]
	v_pk_mul_f32 v[4:5], v[4:5], s[36:37] op_sel_hi:[1,0]
	v_pk_mul_f32 v[6:7], v[6:7], s[36:37] op_sel_hi:[1,0]
	v_cvt_pk_bf16_f32 v140, v12, v13
	v_cvt_pk_bf16_f32 v141, v14, v15
	v_cvt_pk_bf16_f32 v142, v4, v5
	v_cvt_pk_bf16_f32 v143, v6, v7
	v_pk_mul_f32 v[136:137], v[8:9], v[214:215] op_sel:[1,0] op_sel_hi:[0,0]
	v_pk_fma_f32 v[8:9], v[8:9], v[210:211], v[136:137] op_sel:[0,0,0] op_sel_hi:[1,0,1] neg_lo:[0,0,1]
	v_pk_mul_f32 v[136:137], v[10:11], v[214:215] op_sel:[1,1] op_sel_hi:[0,1]
	v_pk_fma_f32 v[10:11], v[10:11], v[210:211], v[136:137] op_sel:[0,1,0] op_sel_hi:[1,1,1] neg_lo:[0,0,1]
	v_pk_mul_f32 v[136:137], v[0:1], v[216:217] op_sel:[1,0] op_sel_hi:[0,0]
	v_pk_fma_f32 v[0:1], v[0:1], v[212:213], v[136:137] op_sel:[0,0,0] op_sel_hi:[1,0,1] neg_lo:[0,0,1]
	v_pk_mul_f32 v[136:137], v[2:3], v[216:217] op_sel:[1,1] op_sel_hi:[0,1]
	v_pk_fma_f32 v[2:3], v[2:3], v[212:213], v[136:137] op_sel:[0,1,0] op_sel_hi:[1,1,1] neg_lo:[0,0,1]
	v_pk_mul_f32 v[8:9], v[8:9], s[36:37] op_sel_hi:[1,0]
	v_pk_mul_f32 v[10:11], v[10:11], s[36:37] op_sel_hi:[1,0]
	v_pk_mul_f32 v[0:1], v[0:1], s[36:37] op_sel_hi:[1,0]
	v_pk_mul_f32 v[2:3], v[2:3], s[36:37] op_sel_hi:[1,0]
	v_cvt_pk_bf16_f32 v144, v8, v9
	v_cvt_pk_bf16_f32 v145, v10, v11
	v_cvt_pk_bf16_f32 v146, v0, v1
	v_cvt_pk_bf16_f32 v147, v2, v3
	s_waitcnt lgkmcnt(0)
	global_store_dwordx4 v130, v[218:221], s[6:7] sc1
	global_store_dwordx4 v130, v[222:225], s[6:7] offset:64 sc1
	s_add_u32 s6, s6, s33
	s_addc_u32 s7, s7, 0
	ds_bpermute_b32 v226, v180, v140
	ds_bpermute_b32 v227, v180, v141
	ds_bpermute_b32 v228, v180, v142
	ds_bpermute_b32 v229, v180, v143
	ds_bpermute_b32 v230, v180, v144
	ds_bpermute_b32 v231, v180, v145
	ds_bpermute_b32 v232, v180, v146
	ds_bpermute_b32 v233, v180, v147
	s_waitcnt lgkmcnt(0)
	global_store_dwordx4 v130, v[226:229], s[6:7] sc1
	global_store_dwordx4 v130, v[230:233], s[6:7] offset:64 sc1
	s_branch .LBB0_638
.Lq3_D:
	v_pk_mul_f32 v[126:127], v[126:127], s[36:37] op_sel_hi:[1,0]
	v_pk_mul_f32 v[128:129], v[128:129], s[36:37] op_sel_hi:[1,0]
	v_pk_mul_f32 v[122:123], v[122:123], s[36:37] op_sel_hi:[1,0]
	v_pk_mul_f32 v[124:125], v[124:125], s[36:37] op_sel_hi:[1,0]
	v_cvt_pk_bf16_f32 v140, v126, v127
	v_cvt_pk_bf16_f32 v141, v128, v129
	v_cvt_pk_bf16_f32 v142, v122, v123
	v_cvt_pk_bf16_f32 v143, v124, v125
	v_pk_mul_f32 v[118:119], v[118:119], s[36:37] op_sel_hi:[1,0]
	v_pk_mul_f32 v[120:121], v[120:121], s[36:37] op_sel_hi:[1,0]
	v_pk_mul_f32 v[114:115], v[114:115], s[36:37] op_sel_hi:[1,0]
	v_pk_mul_f32 v[116:117], v[116:117], s[36:37] op_sel_hi:[1,0]
	v_cvt_pk_bf16_f32 v144, v118, v119
	v_cvt_pk_bf16_f32 v145, v120, v121
	v_cvt_pk_bf16_f32 v146, v114, v115
	v_cvt_pk_bf16_f32 v147, v116, v117
	ds_bpermute_b32 v218, v180, v140
	ds_bpermute_b32 v219, v180, v141
	ds_bpermute_b32 v220, v180, v142
	ds_bpermute_b32 v221, v180, v143
	ds_bpermute_b32 v222, v180, v144
	ds_bpermute_b32 v223, v180, v145
	ds_bpermute_b32 v224, v180, v146
	ds_bpermute_b32 v225, v180, v147
	v_pk_mul_f32 v[108:109], v[108:109], s[36:37] op_sel_hi:[1,0]
	v_pk_mul_f32 v[110:111], v[110:111], s[36:37] op_sel_hi:[1,0]
	v_pk_mul_f32 v[104:105], v[104:105], s[36:37] op_sel_hi:[1,0]
	v_pk_mul_f32 v[106:107], v[106:107], s[36:37] op_sel_hi:[1,0]
	v_cvt_pk_bf16_f32 v140, v108, v109
	v_cvt_pk_bf16_f32 v141, v110, v111
	v_cvt_pk_bf16_f32 v142, v104, v105
	v_cvt_pk_bf16_f32 v143, v106, v107
	v_pk_mul_f32 v[100:101], v[100:101], s[36:37] op_sel_hi:[1,0]
	v_pk_mul_f32 v[102:103], v[102:103], s[36:37] op_sel_hi:[1,0]
	v_pk_mul_f32 v[96:97], v[96:97], s[36:37] op_sel_hi:[1,0]
	v_pk_mul_f32 v[98:99], v[98:99], s[36:37] op_sel_hi:[1,0]
	v_cvt_pk_bf16_f32 v144, v100, v101
	v_cvt_pk_bf16_f32 v145, v102, v103
	v_cvt_pk_bf16_f32 v146, v96, v97
	v_cvt_pk_bf16_f32 v147, v98, v99
	s_waitcnt lgkmcnt(0)
	global_store_dwordx4 v130, v[218:221], s[6:7] sc1
	global_store_dwordx4 v130, v[222:225], s[6:7] offset:64 sc1
	s_add_u32 s6, s6, s33
	s_addc_u32 s7, s7, 0
	ds_bpermute_b32 v226, v180, v140
	ds_bpermute_b32 v227, v180, v141
	ds_bpermute_b32 v228, v180, v142
	ds_bpermute_b32 v229, v180, v143
	ds_bpermute_b32 v230, v180, v144
	ds_bpermute_b32 v231, v180, v145
	ds_bpermute_b32 v232, v180, v146
	ds_bpermute_b32 v233, v180, v147
	v_pk_mul_f32 v[92:93], v[92:93], s[36:37] op_sel_hi:[1,0]
	v_pk_mul_f32 v[94:95], v[94:95], s[36:37] op_sel_hi:[1,0]
	v_pk_mul_f32 v[88:89], v[88:89], s[36:37] op_sel_hi:[1,0]
	v_pk_mul_f32 v[90:91], v[90:91], s[36:37] op_sel_hi:[1,0]
	v_cvt_pk_bf16_f32 v140, v92, v93
	v_cvt_pk_bf16_f32 v141, v94, v95
	v_cvt_pk_bf16_f32 v142, v88, v89
	v_cvt_pk_bf16_f32 v143, v90, v91
	v_pk_mul_f32 v[84:85], v[84:85], s[36:37] op_sel_hi:[1,0]
	v_pk_mul_f32 v[86:87], v[86:87], s[36:37] op_sel_hi:[1,0]
	v_pk_mul_f32 v[80:81], v[80:81], s[36:37] op_sel_hi:[1,0]
	v_pk_mul_f32 v[82:83], v[82:83], s[36:37] op_sel_hi:[1,0]
	v_cvt_pk_bf16_f32 v144, v84, v85
	v_cvt_pk_bf16_f32 v145, v86, v87
	v_cvt_pk_bf16_f32 v146, v80, v81
	v_cvt_pk_bf16_f32 v147, v82, v83
	s_waitcnt lgkmcnt(0)
	global_store_dwordx4 v130, v[226:229], s[6:7] sc1
	global_store_dwordx4 v130, v[230:233], s[6:7] offset:64 sc1
	s_add_u32 s6, s6, s33
	s_addc_u32 s7, s7, 0
	ds_bpermute_b32 v218, v180, v140
	ds_bpermute_b32 v219, v180, v141
	ds_bpermute_b32 v220, v180, v142
	ds_bpermute_b32 v221, v180, v143
	ds_bpermute_b32 v222, v180, v144
	ds_bpermute_b32 v223, v180, v145
	ds_bpermute_b32 v224, v180, v146
	ds_bpermute_b32 v225, v180, v147
	v_pk_mul_f32 v[76:77], v[76:77], s[36:37] op_sel_hi:[1,0]
	v_pk_mul_f32 v[78:79], v[78:79], s[36:37] op_sel_hi:[1,0]
	v_pk_mul_f32 v[72:73], v[72:73], s[36:37] op_sel_hi:[1,0]
	v_pk_mul_f32 v[74:75], v[74:75], s[36:37] op_sel_hi:[1,0]
	v_cvt_pk_bf16_f32 v140, v76, v77
	v_cvt_pk_bf16_f32 v141, v78, v79
	v_cvt_pk_bf16_f32 v142, v72, v73
	v_cvt_pk_bf16_f32 v143, v74, v75
	v_pk_mul_f32 v[68:69], v[68:69], s[36:37] op_sel_hi:[1,0]
	v_pk_mul_f32 v[70:71], v[70:71], s[36:37] op_sel_hi:[1,0]
	v_pk_mul_f32 v[64:65], v[64:65], s[36:37] op_sel_hi:[1,0]
	v_pk_mul_f32 v[66:67], v[66:67], s[36:37] op_sel_hi:[1,0]
	v_cvt_pk_bf16_f32 v144, v68, v69
	v_cvt_pk_bf16_f32 v145, v70, v71
	v_cvt_pk_bf16_f32 v146, v64, v65
	v_cvt_pk_bf16_f32 v147, v66, v67
	s_waitcnt lgkmcnt(0)
	global_store_dwordx4 v130, v[218:221], s[6:7] sc1
	global_store_dwordx4 v130, v[222:225], s[6:7] offset:64 sc1
	s_add_u32 s6, s6, s33
	s_addc_u32 s7, s7, 0
	ds_bpermute_b32 v226, v180, v140
	ds_bpermute_b32 v227, v180, v141
	ds_bpermute_b32 v228, v180, v142
	ds_bpermute_b32 v229, v180, v143
	ds_bpermute_b32 v230, v180, v144
	ds_bpermute_b32 v231, v180, v145
	ds_bpermute_b32 v232, v180, v146
	ds_bpermute_b32 v233, v180, v147
	v_pk_mul_f32 v[60:61], v[60:61], s[36:37] op_sel_hi:[1,0]
	v_pk_mul_f32 v[62:63], v[62:63], s[36:37] op_sel_hi:[1,0]
	v_pk_mul_f32 v[56:57], v[56:57], s[36:37] op_sel_hi:[1,0]
	v_pk_mul_f32 v[58:59], v[58:59], s[36:37] op_sel_hi:[1,0]
	v_cvt_pk_bf16_f32 v140, v60, v61
	v_cvt_pk_bf16_f32 v141, v62, v63
	v_cvt_pk_bf16_f32 v142, v56, v57
	v_cvt_pk_bf16_f32 v143, v58, v59
	v_pk_mul_f32 v[52:53], v[52:53], s[36:37] op_sel_hi:[1,0]
	v_pk_mul_f32 v[54:55], v[54:55], s[36:37] op_sel_hi:[1,0]
	v_pk_mul_f32 v[48:49], v[48:49], s[36:37] op_sel_hi:[1,0]
	v_pk_mul_f32 v[50:51], v[50:51], s[36:37] op_sel_hi:[1,0]
	v_cvt_pk_bf16_f32 v144, v52, v53
	v_cvt_pk_bf16_f32 v145, v54, v55
	v_cvt_pk_bf16_f32 v146, v48, v49
	v_cvt_pk_bf16_f32 v147, v50, v51
	s_waitcnt lgkmcnt(0)
	global_store_dwordx4 v130, v[226:229], s[6:7] sc1
	global_store_dwordx4 v130, v[230:233], s[6:7] offset:64 sc1
	s_add_u32 s6, s6, s34
	s_addc_u32 s7, s7, 0
	ds_bpermute_b32 v218, v180, v140
	ds_bpermute_b32 v219, v180, v141
	ds_bpermute_b32 v220, v180, v142
	ds_bpermute_b32 v221, v180, v143
	ds_bpermute_b32 v222, v180, v144
	ds_bpermute_b32 v223, v180, v145
	ds_bpermute_b32 v224, v180, v146
	ds_bpermute_b32 v225, v180, v147
	v_pk_mul_f32 v[44:45], v[44:45], s[36:37] op_sel_hi:[1,0]
	v_pk_mul_f32 v[46:47], v[46:47], s[36:37] op_sel_hi:[1,0]
	v_pk_mul_f32 v[40:41], v[40:41], s[36:37] op_sel_hi:[1,0]
	v_pk_mul_f32 v[42:43], v[42:43], s[36:37] op_sel_hi:[1,0]
	v_cvt_pk_bf16_f32 v140, v44, v45
	v_cvt_pk_bf16_f32 v141, v46, v47
	v_cvt_pk_bf16_f32 v142, v40, v41
	v_cvt_pk_bf16_f32 v143, v42, v43
	v_pk_mul_f32 v[36:37], v[36:37], s[36:37] op_sel_hi:[1,0]
	v_pk_mul_f32 v[38:39], v[38:39], s[36:37] op_sel_hi:[1,0]
	v_pk_mul_f32 v[32:33], v[32:33], s[36:37] op_sel_hi:[1,0]
	v_pk_mul_f32 v[34:35], v[34:35], s[36:37] op_sel_hi:[1,0]
	v_cvt_pk_bf16_f32 v144, v36, v37
	v_cvt_pk_bf16_f32 v145, v38, v39
	v_cvt_pk_bf16_f32 v146, v32, v33
	v_cvt_pk_bf16_f32 v147, v34, v35
	s_waitcnt lgkmcnt(0)
	global_store_dwordx4 v130, v[218:221], s[6:7] sc1
	global_store_dwordx4 v130, v[222:225], s[6:7] offset:64 sc1
	s_add_u32 s6, s6, s33
	s_addc_u32 s7, s7, 0
	ds_bpermute_b32 v226, v180, v140
	ds_bpermute_b32 v227, v180, v141
	ds_bpermute_b32 v228, v180, v142
	ds_bpermute_b32 v229, v180, v143
	ds_bpermute_b32 v230, v180, v144
	ds_bpermute_b32 v231, v180, v145
	ds_bpermute_b32 v232, v180, v146
	ds_bpermute_b32 v233, v180, v147
	v_pk_mul_f32 v[28:29], v[28:29], s[36:37] op_sel_hi:[1,0]
	v_pk_mul_f32 v[30:31], v[30:31], s[36:37] op_sel_hi:[1,0]
	v_pk_mul_f32 v[24:25], v[24:25], s[36:37] op_sel_hi:[1,0]
	v_pk_mul_f32 v[26:27], v[26:27], s[36:37] op_sel_hi:[1,0]
	v_cvt_pk_bf16_f32 v140, v28, v29
	v_cvt_pk_bf16_f32 v141, v30, v31
	v_cvt_pk_bf16_f32 v142, v24, v25
	v_cvt_pk_bf16_f32 v143, v26, v27
	v_pk_mul_f32 v[20:21], v[20:21], s[36:37] op_sel_hi:[1,0]
	v_pk_mul_f32 v[22:23], v[22:23], s[36:37] op_sel_hi:[1,0]
	v_pk_mul_f32 v[16:17], v[16:17], s[36:37] op_sel_hi:[1,0]
	v_pk_mul_f32 v[18:19], v[18:19], s[36:37] op_sel_hi:[1,0]
	v_cvt_pk_bf16_f32 v144, v20, v21
	v_cvt_pk_bf16_f32 v145, v22, v23
	v_cvt_pk_bf16_f32 v146, v16, v17
	v_cvt_pk_bf16_f32 v147, v18, v19
	s_waitcnt lgkmcnt(0)
	global_store_dwordx4 v130, v[226:229], s[6:7] sc1
	global_store_dwordx4 v130, v[230:233], s[6:7] offset:64 sc1
	s_add_u32 s6, s6, s33
	s_addc_u32 s7, s7, 0
	ds_bpermute_b32 v218, v180, v140
	ds_bpermute_b32 v219, v180, v141
	ds_bpermute_b32 v220, v180, v142
	ds_bpermute_b32 v221, v180, v143
	ds_bpermute_b32 v222, v180, v144
	ds_bpermute_b32 v223, v180, v145
	ds_bpermute_b32 v224, v180, v146
	ds_bpermute_b32 v225, v180, v147
	v_pk_mul_f32 v[12:13], v[12:13], s[36:37] op_sel_hi:[1,0]
	v_pk_mul_f32 v[14:15], v[14:15], s[36:37] op_sel_hi:[1,0]
	v_pk_mul_f32 v[4:5], v[4:5], s[36:37] op_sel_hi:[1,0]
	v_pk_mul_f32 v[6:7], v[6:7], s[36:37] op_sel_hi:[1,0]
	v_cvt_pk_bf16_f32 v140, v12, v13
	v_cvt_pk_bf16_f32 v141, v14, v15
	v_cvt_pk_bf16_f32 v142, v4, v5
	v_cvt_pk_bf16_f32 v143, v6, v7
	v_pk_mul_f32 v[8:9], v[8:9], s[36:37] op_sel_hi:[1,0]
	v_pk_mul_f32 v[10:11], v[10:11], s[36:37] op_sel_hi:[1,0]
	v_pk_mul_f32 v[0:1], v[0:1], s[36:37] op_sel_hi:[1,0]
	v_pk_mul_f32 v[2:3], v[2:3], s[36:37] op_sel_hi:[1,0]
	v_cvt_pk_bf16_f32 v144, v8, v9
	v_cvt_pk_bf16_f32 v145, v10, v11
	v_cvt_pk_bf16_f32 v146, v0, v1
	v_cvt_pk_bf16_f32 v147, v2, v3
	s_waitcnt lgkmcnt(0)
	global_store_dwordx4 v130, v[218:221], s[6:7] sc1
	global_store_dwordx4 v130, v[222:225], s[6:7] offset:64 sc1
	s_add_u32 s6, s6, s33
	s_addc_u32 s7, s7, 0
	ds_bpermute_b32 v226, v180, v140
	ds_bpermute_b32 v227, v180, v141
	ds_bpermute_b32 v228, v180, v142
	ds_bpermute_b32 v229, v180, v143
	ds_bpermute_b32 v230, v180, v144
	ds_bpermute_b32 v231, v180, v145
	ds_bpermute_b32 v232, v180, v146
	ds_bpermute_b32 v233, v180, v147
	s_waitcnt lgkmcnt(0)
	global_store_dwordx4 v130, v[226:229], s[6:7] sc1
	global_store_dwordx4 v130, v[230:233], s[6:7] offset:64 sc1
	s_branch .LBB0_638
